# MoBA K tiles stored fragment-major by the P1 epilogue; pass-1 and gathered loops load K fragments straight into MFMA operand registers (no LDS staging for K); P6 epilogue loads pipelined
# speedup vs baseline: 1.5804x; 1.5804x over previous
; #define PG8_STAGE(bufoff, gbase, voff) do { _Pragma("unroll") for (int _i = 0; _i < 2; ++_i) \
;         __builtin_amdgcn_global_load_lds((const unsigned*)((const char*)(gbase) + (voff)[_i]), (PG8_LAS unsigned*)(lds + (bufoff) + ldsw + _i * 8192), 16, 0, 0); } while (0)
; #define PG8_LDA(dst, b, h) do { _Pragma("unroll") for (int m = 0; m < 4; ++m) _Pragma("unroll") for (int k = 0; k < 2; ++k) dst[m][k] = *(const PG8_LAS bf16x8*)(lds + PG8_SA(b, h) + aoff + m * 2048 + k * 1024); } while (0)
; #define PG8_LDB(dst, b, h) do { _Pragma("unroll") for (int n = 0; n < 2; ++n) _Pragma("unroll") for (int k = 0; k < 2; ++k) dst[n][k] = *(const PG8_LAS bf16x8*)(lds + PG8_SB(b, h) + boff + n * 2048 + k * 1024); } while (0)
; #define PG8_MMA(ai, bj, At, Bt) do { __builtin_amdgcn_s_setprio(1); _Pragma("unroll") for (int m = 0; m < 4; ++m) _Pragma("unroll") for (int n = 0; n < 2; ++n) _Pragma("unroll") for (int k = 0; k < 2; ++k) \
;         acc[ai][bj][m][n] = __builtin_amdgcn_mfma_f32_16x16x32_bf16(Bt[n][k], At[m][k], acc[ai][bj][m][n], 0, 0, 0); __builtin_amdgcn_s_setprio(0); } while (0)
; #define PG8_WAIT_V(n) asm volatile("s_waitcnt vmcnt(" #n ")" ::: "memory")
; #define PG8_WAIT_L(n) asm volatile("s_waitcnt lgkmcnt(" #n ")" ::: "memory")
; #define PG8_BAR __builtin_amdgcn_s_barrier()
; #define PG8_SCHED __builtin_amdgcn_sched_barrier(0)
; template <class Epi, class Sched, bool ALIGN_EPI = false, bool SP2 = false>
; __device__ __forceinline__ void gemm_phase(PG8_LAS unsigned char* lds, const Gemm g, const Sched& S, const Epi& E) {
;     ...
;             PG8_LDB(B0, 0, 0); PG8_LDB(B1, 0, 1); PG8_SCHED; PG8_LDA(At, 0, 0); PG8_STAGE(PG8_SA(1, 1), a1 + hstep, voffA);
;             PG8_WAIT_V(8); PG8_WAIT_L(0); PG8_BAR; PG8_MMA(0, 0, At, B0); PG8_MMA(0, 1, At, B1); PG8_BAR; PG8_SCHED;
;             PG8_LDA(At, 0, 1); PG8_STAGE(PG8_SB(0, 0), b2, voffB); PG8_STAGE(PG8_SB(0, 1), b2 + hstep, voffB); PG8_STAGE(PG8_SA(0, 0), a2, voffA);
;             PG8_WAIT_V(8); PG8_WAIT_L(0); PG8_BAR; PG8_MMA(1, 0, At, B0); PG8_MMA(1, 1, At, B1); PG8_BAR; PG8_SCHED;
.LBB0_387:
	ds_read_b128 v[128:131], v171
	ds_read_b128 v[132:135], v171 offset:1024
	ds_read_b128 v[136:139], v171 offset:2048
	ds_read_b128 v[182:185], v171 offset:3072
	ds_read_b128 v[186:189], v173
	ds_read_b128 v[190:193], v173 offset:1024
	ds_read_b128 v[194:197], v173 offset:2048
	ds_read_b128 v[198:201], v173 offset:3072
	s_add_u32 s77, s82, 0xfffc0080
	s_addc_u32 s84, s83, -1
	s_cmp_eq_u32 s75, 12
	s_cselect_b32 s87, s2, s84
	s_cselect_b32 s86, s7, s77
	s_cselect_b32 s85, s12, s45
	s_cselect_b32 s84, s17, s44
	v_lshl_add_u64 v[168:169], s[82:83], 0, v[158:159]
	s_add_i32 m0, s11, 0xc000
	ds_read_b128 v[202:205], v175
	ds_read_b128 v[206:209], v175 offset:1024
	ds_read_b128 v[210:213], v175 offset:2048
	ds_read_b128 v[214:217], v175 offset:3072
	ds_read_b128 v[218:221], v175 offset:4096
	ds_read_b128 v[226:229], v175 offset:5120
	ds_read_b128 v[230:233], v175 offset:6144
	ds_read_b128 v[236:239], v175 offset:7168
	global_load_lds_dwordx4 v[168:169], off
	v_lshl_add_u64 v[168:169], s[82:83], 0, v[160:161]
	s_add_i32 m0, s11, 0xe000
	s_nop 0
	global_load_lds_dwordx4 v[168:169], off
	s_waitcnt vmcnt(8)
	s_waitcnt lgkmcnt(0)
	s_barrier
	s_setprio 1
	s_waitcnt lgkmcnt(0)
	v_mfma_f32_16x16x32_bf16 v[124:127], v[128:131], v[202:205], v[124:127]
	v_mfma_f32_16x16x32_bf16 v[116:119], v[136:139], v[202:205], v[116:119]
	v_mfma_f32_16x16x32_bf16 v[108:111], v[128:131], v[210:213], v[108:111]
	v_mfma_f32_16x16x32_bf16 v[100:103], v[136:139], v[210:213], v[100:103]
	v_mfma_f32_16x16x32_bf16 v[92:95], v[128:131], v[218:221], v[92:95]
	v_mfma_f32_16x16x32_bf16 v[84:87], v[136:139], v[218:221], v[84:87]
	v_mfma_f32_16x16x32_bf16 v[76:79], v[128:131], v[230:233], v[76:79]
	v_mfma_f32_16x16x32_bf16 v[68:71], v[136:139], v[230:233], v[68:71]
	v_mfma_f32_16x16x32_bf16 v[124:127], v[132:135], v[206:209], v[124:127]
	v_mfma_f32_16x16x32_bf16 v[116:119], v[182:185], v[206:209], v[116:119]
	v_mfma_f32_16x16x32_bf16 v[108:111], v[132:135], v[214:217], v[108:111]
	v_mfma_f32_16x16x32_bf16 v[100:103], v[182:185], v[214:217], v[100:103]
	v_mfma_f32_16x16x32_bf16 v[92:95], v[132:135], v[226:229], v[92:95]
	v_mfma_f32_16x16x32_bf16 v[84:87], v[182:185], v[226:229], v[84:87]
	v_mfma_f32_16x16x32_bf16 v[76:79], v[132:135], v[236:239], v[76:79]
	v_mfma_f32_16x16x32_bf16 v[68:71], v[182:185], v[236:239], v[68:71]
	s_setprio 0
	s_setprio 1
	v_mfma_f32_16x16x32_bf16 v[120:123], v[186:189], v[202:205], v[120:123]
	v_mfma_f32_16x16x32_bf16 v[112:115], v[194:197], v[202:205], v[112:115]
	v_mfma_f32_16x16x32_bf16 v[104:107], v[186:189], v[210:213], v[104:107]
	v_mfma_f32_16x16x32_bf16 v[96:99], v[194:197], v[210:213], v[96:99]
	v_mfma_f32_16x16x32_bf16 v[88:91], v[186:189], v[218:221], v[88:91]
	v_mfma_f32_16x16x32_bf16 v[80:83], v[194:197], v[218:221], v[80:83]
	v_mfma_f32_16x16x32_bf16 v[72:75], v[186:189], v[230:233], v[72:75]
	v_mfma_f32_16x16x32_bf16 v[64:67], v[194:197], v[230:233], v[64:67]
	v_mfma_f32_16x16x32_bf16 v[120:123], v[190:193], v[206:209], v[120:123]
	v_mfma_f32_16x16x32_bf16 v[112:115], v[198:201], v[206:209], v[112:115]
	v_mfma_f32_16x16x32_bf16 v[104:107], v[190:193], v[214:217], v[104:107]
	v_mfma_f32_16x16x32_bf16 v[96:99], v[198:201], v[214:217], v[96:99]
	v_mfma_f32_16x16x32_bf16 v[88:91], v[190:193], v[226:229], v[88:91]
	v_mfma_f32_16x16x32_bf16 v[80:83], v[198:201], v[226:229], v[80:83]
	v_mfma_f32_16x16x32_bf16 v[72:75], v[190:193], v[236:239], v[72:75]
	v_mfma_f32_16x16x32_bf16 v[64:67], v[198:201], v[236:239], v[64:67]
	s_setprio 0
	s_barrier
	s_add_i32 s77, s31, s71
	v_lshl_add_u64 v[168:169], s[84:85], 0, v[142:143]
	s_mov_b32 m0, s77
	ds_read_b128 v[202:205], v175 offset:16384
	ds_read_b128 v[206:209], v175 offset:17408
	ds_read_b128 v[210:213], v175 offset:18432
	ds_read_b128 v[214:217], v175 offset:19456
	ds_read_b128 v[218:221], v175 offset:20480
	ds_read_b128 v[226:229], v175 offset:21504
	ds_read_b128 v[230:233], v175 offset:22528
	ds_read_b128 v[236:239], v175 offset:23552
	global_load_lds_dwordx4 v[168:169], off
	s_add_i32 m0, s77, 0x2000
	s_add_u32 s90, s84, 0x40000
	v_lshl_add_u64 v[178:179], s[84:85], 0, v[146:147]
	s_addc_u32 s91, s85, 0
	s_add_i32 s77, s22, s71
	global_load_lds_dwordx4 v[178:179], off
	v_lshl_add_u64 v[222:223], s[90:91], 0, v[142:143]
	s_mov_b32 m0, s77
	v_lshl_add_u64 v[240:241], s[86:87], 0, v[144:145]
	global_load_lds_dwordx4 v[222:223], off
	v_lshl_add_u64 v[222:223], s[90:91], 0, v[146:147]
	s_add_i32 m0, s77, 0x2000
	s_nop 0
	global_load_lds_dwordx4 v[222:223], off
	v_lshl_add_u64 v[222:223], s[86:87], 0, v[140:141]
	s_mov_b32 m0, s11
	s_nop 0
	global_load_lds_dwordx4 v[222:223], off
	s_mov_b32 m0, s89
	s_nop 0
	global_load_lds_dwordx4 v[240:241], off
	s_waitcnt vmcnt(8)
	s_waitcnt lgkmcnt(0)
	s_barrier
; #define PG8_STAGE(bufoff, gbase, voff) do { _Pragma("unroll") for (int _i = 0; _i < 2; ++_i) \
;         __builtin_amdgcn_global_load_lds((const unsigned*)((const char*)(gbase) + (voff)[_i]), (PG8_LAS unsigned*)(lds + (bufoff) + ldsw + _i * 8192), 16, 0, 0); } while (0)
; #define PG8_LDA(dst, b, h) do { _Pragma("unroll") for (int m = 0; m < 4; ++m) _Pragma("unroll") for (int k = 0; k < 2; ++k) dst[m][k] = *(const PG8_LAS bf16x8*)(lds + PG8_SA(b, h) + aoff + m * 2048 + k * 1024); } while (0)
; #define PG8_LDB(dst, b, h) do { _Pragma("unroll") for (int n = 0; n < 2; ++n) _Pragma("unroll") for (int k = 0; k < 2; ++k) dst[n][k] = *(const PG8_LAS bf16x8*)(lds + PG8_SB(b, h) + boff + n * 2048 + k * 1024); } while (0)
; #define PG8_MMA(ai, bj, At, Bt) do { __builtin_amdgcn_s_setprio(1); _Pragma("unroll") for (int m = 0; m < 4; ++m) _Pragma("unroll") for (int n = 0; n < 2; ++n) _Pragma("unroll") for (int k = 0; k < 2; ++k) \
;         acc[ai][bj][m][n] = __builtin_amdgcn_mfma_f32_16x16x32_bf16(Bt[n][k], At[m][k], acc[ai][bj][m][n], 0, 0, 0); __builtin_amdgcn_s_setprio(0); } while (0)
; #define PG8_WAIT_V(n) asm volatile("s_waitcnt vmcnt(" #n ")" ::: "memory")
; #define PG8_WAIT_L(n) asm volatile("s_waitcnt lgkmcnt(" #n ")" ::: "memory")
; #define PG8_BAR __builtin_amdgcn_s_barrier()
; #define PG8_SCHED __builtin_amdgcn_sched_barrier(0)
; template <class Epi, class Sched, bool ALIGN_EPI = false, bool SP2 = false>
; __device__ __forceinline__ void gemm_phase(PG8_LAS unsigned char* lds, const Gemm g, const Sched& S, const Epi& E) {
;     ...
;             PG8_WAIT_V(8); PG8_WAIT_L(0); PG8_BAR; PG8_MMA(1, 0, At, B0); PG8_MMA(1, 1, At, B1); PG8_BAR; PG8_SCHED;
;             PG8_LDB(B0, 1, 0); PG8_LDB(B1, 1, 1); PG8_SCHED; PG8_LDA(At, 1, 0); PG8_STAGE(PG8_SA(0, 1), a2 + hstep, voffA);
;             PG8_WAIT_V(8); PG8_WAIT_L(0); PG8_BAR; PG8_MMA(0, 0, At, B0); PG8_MMA(0, 1, At, B1); PG8_BAR; PG8_SCHED;
	s_setprio 1
	s_waitcnt lgkmcnt(0)
	v_mfma_f32_16x16x32_bf16 v[60:63], v[128:131], v[202:205], v[60:63]
	v_mfma_f32_16x16x32_bf16 v[52:55], v[136:139], v[202:205], v[52:55]
	v_mfma_f32_16x16x32_bf16 v[44:47], v[128:131], v[210:213], v[44:47]
	v_mfma_f32_16x16x32_bf16 v[36:39], v[136:139], v[210:213], v[36:39]
	v_mfma_f32_16x16x32_bf16 v[28:31], v[128:131], v[218:221], v[28:31]
	v_mfma_f32_16x16x32_bf16 v[20:23], v[136:139], v[218:221], v[20:23]
	v_mfma_f32_16x16x32_bf16 v[12:15], v[128:131], v[230:233], v[12:15]
	v_mfma_f32_16x16x32_bf16 v[4:7], v[136:139], v[230:233], v[4:7]
	v_mfma_f32_16x16x32_bf16 v[60:63], v[132:135], v[206:209], v[60:63]
	v_mfma_f32_16x16x32_bf16 v[52:55], v[182:185], v[206:209], v[52:55]
	v_mfma_f32_16x16x32_bf16 v[44:47], v[132:135], v[214:217], v[44:47]
	v_mfma_f32_16x16x32_bf16 v[36:39], v[182:185], v[214:217], v[36:39]
	v_mfma_f32_16x16x32_bf16 v[28:31], v[132:135], v[226:229], v[28:31]
	v_mfma_f32_16x16x32_bf16 v[20:23], v[182:185], v[226:229], v[20:23]
	v_mfma_f32_16x16x32_bf16 v[12:15], v[132:135], v[236:239], v[12:15]
	v_mfma_f32_16x16x32_bf16 v[4:7], v[182:185], v[236:239], v[4:7]
	s_setprio 0
	s_setprio 1
	v_mfma_f32_16x16x32_bf16 v[56:59], v[186:189], v[202:205], v[56:59]
	v_mfma_f32_16x16x32_bf16 v[48:51], v[194:197], v[202:205], v[48:51]
	v_mfma_f32_16x16x32_bf16 v[40:43], v[186:189], v[210:213], v[40:43]
	v_mfma_f32_16x16x32_bf16 v[32:35], v[194:197], v[210:213], v[32:35]
	v_mfma_f32_16x16x32_bf16 v[24:27], v[186:189], v[218:221], v[24:27]
	v_mfma_f32_16x16x32_bf16 v[16:19], v[194:197], v[218:221], v[16:19]
	v_mfma_f32_16x16x32_bf16 v[8:11], v[186:189], v[230:233], v[8:11]
	v_mfma_f32_16x16x32_bf16 v[0:3], v[194:197], v[230:233], v[0:3]
	v_mfma_f32_16x16x32_bf16 v[56:59], v[190:193], v[206:209], v[56:59]
	v_mfma_f32_16x16x32_bf16 v[48:51], v[198:201], v[206:209], v[48:51]
	v_mfma_f32_16x16x32_bf16 v[40:43], v[190:193], v[214:217], v[40:43]
	v_mfma_f32_16x16x32_bf16 v[32:35], v[198:201], v[214:217], v[32:35]
	v_mfma_f32_16x16x32_bf16 v[24:27], v[190:193], v[226:229], v[24:27]
	v_mfma_f32_16x16x32_bf16 v[16:19], v[198:201], v[226:229], v[16:19]
	v_mfma_f32_16x16x32_bf16 v[8:11], v[190:193], v[236:239], v[8:11]
	v_mfma_f32_16x16x32_bf16 v[0:3], v[198:201], v[236:239], v[0:3]
	s_setprio 0
	s_barrier
	s_add_i32 s77, 0, 0x18000
	v_add_u32_e32 v148, s77, v167
	s_add_i32 s88, 0, 0x1c000
	ds_read_b128 v[128:131], v148
	ds_read_b128 v[132:135], v148 offset:1024
	ds_read_b128 v[136:139], v148 offset:2048
	ds_read_b128 v[182:185], v148 offset:3072
	v_add_u32_e32 v148, s88, v167
	ds_read_b128 v[186:189], v148
	ds_read_b128 v[190:193], v148 offset:1024
	ds_read_b128 v[194:197], v148 offset:2048
	ds_read_b128 v[198:201], v148 offset:3072
	s_add_u32 s86, s86, 0x40000
	s_addc_u32 s87, s87, 0
	s_mov_b32 m0, s95
	v_lshl_add_u64 v[242:243], s[86:87], 0, v[140:141]
	ds_read_b128 v[202:205], v175 offset:32768
	ds_read_b128 v[206:209], v175 offset:33792
	ds_read_b128 v[210:213], v175 offset:34816
	ds_read_b128 v[214:217], v175 offset:35840
	ds_read_b128 v[218:221], v175 offset:36864
	ds_read_b128 v[226:229], v175 offset:37888
	ds_read_b128 v[230:233], v175 offset:38912
	ds_read_b128 v[236:239], v175 offset:39936
	global_load_lds_dwordx4 v[242:243], off
	v_lshl_add_u64 v[242:243], s[86:87], 0, v[144:145]
	s_mov_b32 m0, s96
	s_nop 0
	global_load_lds_dwordx4 v[242:243], off
	s_waitcnt vmcnt(8)
	s_waitcnt lgkmcnt(0)
	s_barrier
	s_setprio 1
	s_waitcnt lgkmcnt(0)
	v_mfma_f32_16x16x32_bf16 v[124:127], v[128:131], v[202:205], v[124:127]
	v_mfma_f32_16x16x32_bf16 v[116:119], v[136:139], v[202:205], v[116:119]
	v_mfma_f32_16x16x32_bf16 v[108:111], v[128:131], v[210:213], v[108:111]
	v_mfma_f32_16x16x32_bf16 v[100:103], v[136:139], v[210:213], v[100:103]
	v_mfma_f32_16x16x32_bf16 v[92:95], v[128:131], v[218:221], v[92:95]
	v_mfma_f32_16x16x32_bf16 v[84:87], v[136:139], v[218:221], v[84:87]
	v_mfma_f32_16x16x32_bf16 v[76:79], v[128:131], v[230:233], v[76:79]
	v_mfma_f32_16x16x32_bf16 v[68:71], v[136:139], v[230:233], v[68:71]
	v_mfma_f32_16x16x32_bf16 v[124:127], v[132:135], v[206:209], v[124:127]
	v_mfma_f32_16x16x32_bf16 v[116:119], v[182:185], v[206:209], v[116:119]
	v_mfma_f32_16x16x32_bf16 v[108:111], v[132:135], v[214:217], v[108:111]
	v_mfma_f32_16x16x32_bf16 v[100:103], v[182:185], v[214:217], v[100:103]
	v_mfma_f32_16x16x32_bf16 v[92:95], v[132:135], v[226:229], v[92:95]
	v_mfma_f32_16x16x32_bf16 v[84:87], v[182:185], v[226:229], v[84:87]
	v_mfma_f32_16x16x32_bf16 v[76:79], v[132:135], v[236:239], v[76:79]
	v_mfma_f32_16x16x32_bf16 v[68:71], v[182:185], v[236:239], v[68:71]
	s_setprio 0
	s_setprio 1
	v_mfma_f32_16x16x32_bf16 v[120:123], v[186:189], v[202:205], v[120:123]
	v_mfma_f32_16x16x32_bf16 v[112:115], v[194:197], v[202:205], v[112:115]
	v_mfma_f32_16x16x32_bf16 v[104:107], v[186:189], v[210:213], v[104:107]
	v_mfma_f32_16x16x32_bf16 v[96:99], v[194:197], v[210:213], v[96:99]
	v_mfma_f32_16x16x32_bf16 v[88:91], v[186:189], v[218:221], v[88:91]
	v_mfma_f32_16x16x32_bf16 v[80:83], v[194:197], v[218:221], v[80:83]
	v_mfma_f32_16x16x32_bf16 v[72:75], v[186:189], v[230:233], v[72:75]
	v_mfma_f32_16x16x32_bf16 v[64:67], v[194:197], v[230:233], v[64:67]
	v_mfma_f32_16x16x32_bf16 v[120:123], v[190:193], v[206:209], v[120:123]
	v_mfma_f32_16x16x32_bf16 v[112:115], v[198:201], v[206:209], v[112:115]
	v_mfma_f32_16x16x32_bf16 v[104:107], v[190:193], v[214:217], v[104:107]
	v_mfma_f32_16x16x32_bf16 v[96:99], v[198:201], v[214:217], v[96:99]
	v_mfma_f32_16x16x32_bf16 v[88:91], v[190:193], v[226:229], v[88:91]
	v_mfma_f32_16x16x32_bf16 v[80:83], v[198:201], v[226:229], v[80:83]
	v_mfma_f32_16x16x32_bf16 v[72:75], v[190:193], v[236:239], v[72:75]
	v_mfma_f32_16x16x32_bf16 v[64:67], v[198:201], v[236:239], v[64:67]
	s_setprio 0
	s_barrier
; #define PG8_STAGE(bufoff, gbase, voff) do { _Pragma("unroll") for (int _i = 0; _i < 2; ++_i) \
;         __builtin_amdgcn_global_load_lds((const unsigned*)((const char*)(gbase) + (voff)[_i]), (PG8_LAS unsigned*)(lds + (bufoff) + ldsw + _i * 8192), 16, 0, 0); } while (0)
; #define PG8_LDA(dst, b, h) do { _Pragma("unroll") for (int m = 0; m < 4; ++m) _Pragma("unroll") for (int k = 0; k < 2; ++k) dst[m][k] = *(const PG8_LAS bf16x8*)(lds + PG8_SA(b, h) + aoff + m * 2048 + k * 1024); } while (0)
; #define PG8_MMA(ai, bj, At, Bt) do { __builtin_amdgcn_s_setprio(1); _Pragma("unroll") for (int m = 0; m < 4; ++m) _Pragma("unroll") for (int n = 0; n < 2; ++n) _Pragma("unroll") for (int k = 0; k < 2; ++k) \
;         acc[ai][bj][m][n] = __builtin_amdgcn_mfma_f32_16x16x32_bf16(Bt[n][k], At[m][k], acc[ai][bj][m][n], 0, 0, 0); __builtin_amdgcn_s_setprio(0); } while (0)
; #define PG8_WAIT_V(n) asm volatile("s_waitcnt vmcnt(" #n ")" ::: "memory")
; #define PG8_WAIT_L(n) asm volatile("s_waitcnt lgkmcnt(" #n ")" ::: "memory")
; #define PG8_BAR __builtin_amdgcn_s_barrier()
; #define PG8_SCHED __builtin_amdgcn_sched_barrier(0)
; template <class Epi, class Sched, bool ALIGN_EPI = false, bool SP2 = false>
; __device__ __forceinline__ void gemm_phase(PG8_LAS unsigned char* lds, const Gemm g, const Sched& S, const Epi& E) {
;     ...
;             PG8_LDA(At, 1, 1); PG8_STAGE(PG8_SB(1, 0), b3, voffB); PG8_STAGE(PG8_SB(1, 1), b3 + hstep, voffB); PG8_STAGE(PG8_SA(1, 0), a3, voffA);
;             PG8_WAIT_V(8); PG8_WAIT_L(0); PG8_BAR; PG8_MMA(1, 0, At, B0); PG8_MMA(1, 1, At, B1); PG8_BAR; PG8_SCHED;
;     ...
;         if constexpr (ALIGN_EPI) { if (wr == 0) PG8_BAR; }
	s_add_i32 s77, s77, s71
	v_lshl_add_u64 v[168:169], v[168:169], 0, s[54:55]
	s_mov_b32 m0, s77
	ds_read_b128 v[202:205], v175 offset:49152
	ds_read_b128 v[206:209], v175 offset:50176
	ds_read_b128 v[210:213], v175 offset:51200
	ds_read_b128 v[214:217], v175 offset:52224
	ds_read_b128 v[218:221], v175 offset:53248
	ds_read_b128 v[226:229], v175 offset:54272
	ds_read_b128 v[230:233], v175 offset:55296
	ds_read_b128 v[236:239], v175 offset:56320
	global_load_lds_dwordx4 v[168:169], off
	s_add_i32 m0, s77, 0x2000
	s_add_u32 s84, s84, 0x40080
	v_lshl_add_u64 v[168:169], v[178:179], 0, s[54:55]
	s_addc_u32 s85, s85, 0
	s_add_i32 s77, s88, s71
	global_load_lds_dwordx4 v[168:169], off
	v_lshl_add_u64 v[168:169], s[84:85], 0, v[142:143]
	s_mov_b32 m0, s77
	s_nop 0
	global_load_lds_dwordx4 v[168:169], off
	v_lshl_add_u64 v[168:169], s[84:85], 0, v[146:147]
	s_add_i32 m0, s77, 0x2000
	s_nop 0
	global_load_lds_dwordx4 v[168:169], off
	v_lshl_add_u64 v[168:169], v[222:223], 0, s[54:55]
	s_mov_b32 m0, s33
	s_nop 0
	global_load_lds_dwordx4 v[168:169], off
	v_lshl_add_u64 v[168:169], v[240:241], 0, s[54:55]
	s_mov_b32 m0, s30
	s_nop 0
	global_load_lds_dwordx4 v[168:169], off
	s_waitcnt vmcnt(8)
	s_waitcnt lgkmcnt(0)
	s_barrier
	s_setprio 1
	s_waitcnt lgkmcnt(0)
	v_mfma_f32_16x16x32_bf16 v[60:63], v[128:131], v[202:205], v[60:63]
	v_mfma_f32_16x16x32_bf16 v[52:55], v[136:139], v[202:205], v[52:55]
	v_mfma_f32_16x16x32_bf16 v[44:47], v[128:131], v[210:213], v[44:47]
	v_mfma_f32_16x16x32_bf16 v[36:39], v[136:139], v[210:213], v[36:39]
	v_mfma_f32_16x16x32_bf16 v[28:31], v[128:131], v[218:221], v[28:31]
	v_mfma_f32_16x16x32_bf16 v[20:23], v[136:139], v[218:221], v[20:23]
	v_mfma_f32_16x16x32_bf16 v[12:15], v[128:131], v[230:233], v[12:15]
	v_mfma_f32_16x16x32_bf16 v[4:7], v[136:139], v[230:233], v[4:7]
	v_mfma_f32_16x16x32_bf16 v[60:63], v[132:135], v[206:209], v[60:63]
	v_mfma_f32_16x16x32_bf16 v[52:55], v[182:185], v[206:209], v[52:55]
	v_mfma_f32_16x16x32_bf16 v[44:47], v[132:135], v[214:217], v[44:47]
	v_mfma_f32_16x16x32_bf16 v[36:39], v[182:185], v[214:217], v[36:39]
	v_mfma_f32_16x16x32_bf16 v[28:31], v[132:135], v[226:229], v[28:31]
	v_mfma_f32_16x16x32_bf16 v[20:23], v[182:185], v[226:229], v[20:23]
	v_mfma_f32_16x16x32_bf16 v[12:15], v[132:135], v[236:239], v[12:15]
	v_mfma_f32_16x16x32_bf16 v[4:7], v[182:185], v[236:239], v[4:7]
	s_setprio 0
	s_setprio 1
	v_mfma_f32_16x16x32_bf16 v[56:59], v[186:189], v[202:205], v[56:59]
	v_mfma_f32_16x16x32_bf16 v[48:51], v[194:197], v[202:205], v[48:51]
	v_mfma_f32_16x16x32_bf16 v[40:43], v[186:189], v[210:213], v[40:43]
	v_mfma_f32_16x16x32_bf16 v[32:35], v[194:197], v[210:213], v[32:35]
	v_mfma_f32_16x16x32_bf16 v[24:27], v[186:189], v[218:221], v[24:27]
	v_mfma_f32_16x16x32_bf16 v[16:19], v[194:197], v[218:221], v[16:19]
	v_mfma_f32_16x16x32_bf16 v[8:11], v[186:189], v[230:233], v[8:11]
	v_mfma_f32_16x16x32_bf16 v[0:3], v[194:197], v[230:233], v[0:3]
	v_mfma_f32_16x16x32_bf16 v[56:59], v[190:193], v[206:209], v[56:59]
	v_mfma_f32_16x16x32_bf16 v[48:51], v[198:201], v[206:209], v[48:51]
	v_mfma_f32_16x16x32_bf16 v[40:43], v[190:193], v[214:217], v[40:43]
	v_mfma_f32_16x16x32_bf16 v[32:35], v[198:201], v[214:217], v[32:35]
	v_mfma_f32_16x16x32_bf16 v[24:27], v[190:193], v[226:229], v[24:27]
	v_mfma_f32_16x16x32_bf16 v[16:19], v[198:201], v[226:229], v[16:19]
	v_mfma_f32_16x16x32_bf16 v[8:11], v[190:193], v[236:239], v[8:11]
	v_mfma_f32_16x16x32_bf16 v[0:3], v[198:201], v[236:239], v[0:3]
	s_setprio 0
	s_barrier
	s_add_i32 s75, s75, 2
	s_add_u32 s82, s82, 0x100
	s_addc_u32 s83, s83, 0
	s_add_u32 s44, s44, 0x100
	s_addc_u32 s45, s45, 0
	s_cmp_gt_u32 s75, 13
	s_cbranch_scc0 .LBB0_387
	s_and_b64 vcc, exec, s[56:57]
	s_cbranch_vccz .LBB0_390
	s_barrier

; DI unsigned cvt_pk(float lo, float hi) { const f32x2 v = {lo, hi}; return __builtin_bit_cast(unsigned, __builtin_convertvector(v, bf16v2)); }
;     __device__ __forceinline__ void operator()(const f32x4 (&acc)[2][2][4][2], const Unit& u, int wr, int wc, int fr, int fq) const {
;     ...
;         if (mode == 0) {
;             float g0[8], g1[8], cs0[8], cs1[8];
; #pragma unroll
;             for (int i = 0; i < 8; ++i) { g0[i] = gain[8 * fq + i] * qsc; g1[i] = gain[32 + 8 * fq + i] * qsc; cs0[i] = 0.f; cs1[i] = 0.f; }
; #pragma unroll
;             for (int ai = 0; ai < 2; ++ai)
; #pragma unroll
;                 for (int m = 0; m < 4; ++m) {
;                     const int s = sbase + ai * 128 + m * 16; const float r = ROW_RS(ai, m);
;                     float t0[8], t1[8]; float ss = 0.f;
; #pragma unroll
;                     for (int n = 0; n < 2; ++n)
; #pragma unroll
;                         for (int j = 0; j < 4; ++j) { t0[4 * n + j] = acc[ai][0][m][n][j]; t1[4 * n + j] = acc[ai][1][m][n][j]; }
; #pragma unroll
;                     for (int i = 0; i < 8; ++i) ss += t0[i] * t0[i] + t1[i] * t1[i];
;                     ss += __shfl_xor(ss, 16); ss += __shfl_xor(ss, 32);
;                     const float hr = r * rsqrtf(ss * (r * r) * (1.0f / 64.0f) + NORM_EPS);
;                     const f32x4* cp = (const f32x4*)(cs + (size_t)s * 32 + 8 * fq);
;                     float o0[8], o1[8];
; #pragma unroll
;                     for (int q = 0; q < 4; ++q) { const f32x4 c4 = cp[q];
;                         { const int i = 2 * q; const float a = t0[i] * hr * g0[i], bb = t1[i] * hr * g1[i]; o0[i] = a * c4[0] - bb * c4[1]; o1[i] = bb * c4[0] + a * c4[1]; }
;                         { const int i = 2 * q + 1; const float a = t0[i] * hr * g0[i], bb = t1[i] * hr * g1[i]; o0[i] = a * c4[2] - bb * c4[3]; o1[i] = bb * c4[2] + a * c4[3]; } }
;                     u32x4 w0, w1;
;                     w0.x = cvt_pk(o0[0], o0[1]); w0.y = cvt_pk(o0[2], o0[3]); w0.z = cvt_pk(o0[4], o0[5]); w0.w = cvt_pk(o0[6], o0[7]);
;                     w1.x = cvt_pk(o1[0], o1[1]); w1.y = cvt_pk(o1[2], o1[3]); w1.z = cvt_pk(o1[4], o1[5]); w1.w = cvt_pk(o1[6], o1[7]);
;                     bf16_t* rp = dst + ((bh * SEQ + s) * 64 + 8 * fq);
;                     *(u32x4*)rp = w0; *(u32x4*)(rp + 32) = w1;
.LBB0_422:
	s_andn2_b64 vcc, exec, s[90:91]
	s_cbranch_vccnz .LBB0_442
	s_cmp_lg_u64 s[84:85], 0
	s_cselect_b32 s32, 6, 1
	s_cselect_b32 s90, 0x800, 64
	s_cselect_b32 s75, 0x70, 0
	s_mov_b32 s91, 0
	s_lshl_b32 s77, s75, 4
	v_and_b32_e32 v220, 15, v181
	v_mul_u32_u24_e32 v220, s75, v220
	v_sub_u32_e32 v220, 0, v220
	v_subrev_u32_e32 v222, s77, v220
	v_ashrrev_i32_e32 v221, 31, v220
	v_ashrrev_i32_e32 v223, 31, v222
	v_lshlrev_b32_e32 v129, 2, v150
	global_load_dwordx4 v[130:133], v129, s[86:87] offset:16
	global_load_dwordx4 v[134:137], v129, s[86:87]
	global_load_dwordx4 v[196:199], v129, s[86:87] offset:144
	global_load_dwordx4 v[188:191], v129, s[86:87] offset:128
	v_xor_b32_e32 v129, 16, v181
	s_lshl_b64 s[44:45], s[82:83], 19
	s_add_u32 s6, s6, s44
	s_addc_u32 s7, s7, s45
	v_lshlrev_b32_e32 v148, s32, v150
	v_ashrrev_i32_e32 v169, 31, v168
	v_lshl_add_u64 v[178:179], s[6:7], 0, v[148:149]
	s_waitcnt vmcnt(0)
	v_pk_mul_f32 v[192:193], s[88:89], v[130:131] op_sel_hi:[0,1]
	v_and_b32_e32 v130, 64, v181
	v_add_u32_e32 v201, 64, v130
	v_cmp_lt_i32_e32 vcc, v129, v201
	v_pk_mul_f32 v[194:195], s[88:89], v[196:197] op_sel_hi:[0,1]
	v_pk_mul_f32 v[196:197], s[88:89], v[132:133] op_sel_hi:[0,1]
	v_cndmask_b32_e32 v129, v181, v129, vcc
	v_lshlrev_b32_e32 v206, 2, v129
	v_xor_b32_e32 v129, 32, v181
	v_cmp_lt_i32_e32 vcc, v129, v201
	v_pk_mul_f32 v[132:133], v[120:121], v[120:121]
	v_pk_mul_f32 v[130:131], v[122:123], v[122:123]
	v_cndmask_b32_e32 v129, v181, v129, vcc
	v_pk_fma_f32 v[132:133], v[124:125], v[124:125], v[132:133]
	v_lshlrev_b32_e32 v207, 2, v129
	v_pk_fma_f32 v[130:131], v[126:127], v[126:127], v[130:131]
	v_add_f32_e32 v129, v132, v133
	v_pk_mul_f32 v[186:187], s[88:89], v[188:189] op_sel_hi:[0,1]
	v_pk_mul_f32 v[188:189], s[88:89], v[136:137] op_sel_hi:[0,1]
	v_pk_mul_f32 v[136:137], v[112:113], v[112:113]
	v_add_f32_e32 v129, v130, v129
	v_pk_fma_f32 v[136:137], v[116:117], v[116:117], v[136:137]
	v_add_f32_e32 v129, v131, v129
	v_pk_mul_f32 v[184:185], s[88:89], v[134:135] op_sel_hi:[0,1]
	v_pk_mul_f32 v[134:135], v[114:115], v[114:115]
	v_add_f32_e32 v129, v136, v129
	v_pk_fma_f32 v[134:135], v[118:119], v[118:119], v[134:135]
	v_add_f32_e32 v129, v137, v129
	v_add_f32_e32 v129, v134, v129
	v_add_f32_e32 v129, v135, v129
	ds_bpermute_b32 v130, v206, v129
	v_pk_mul_f32 v[182:183], s[88:89], v[198:199] op_sel_hi:[0,1]
	v_pk_mul_f32 v[190:191], s[88:89], v[190:191] op_sel_hi:[0,1]
	s_waitcnt lgkmcnt(0)
	v_add_f32_e32 v129, v129, v130
	ds_bpermute_b32 v130, v207, v129
	s_waitcnt lgkmcnt(0)
	v_add_f32_e32 v129, v129, v130
	v_mul_f32_e32 v130, v128, v128
	v_mul_f32_e32 v129, v130, v129
	v_fmamk_f32 v129, v129, 0x3c800000, v177
	v_cmp_gt_f32_e32 vcc, s23, v129
	v_mul_f32_e32 v130, 0x4b800000, v129
	s_nop 0
	v_cndmask_b32_e32 v129, v129, v130, vcc
	v_rsq_f32_e32 v129, v129
	s_nop 0
	v_mul_f32_e32 v130, 0x45800000, v129
	v_cndmask_b32_e32 v129, v129, v130, vcc
	v_mul_f32_e32 v148, v128, v129
	v_lshlrev_b64 v[128:129], 8, v[168:169]
	v_lshl_add_u64 v[198:199], v[152:153], 0, v[128:129]
	global_load_dwordx4 v[128:131], v[198:199], off offset:48
	global_load_dwordx4 v[132:135], v[198:199], off offset:32
	global_load_dwordx4 v[136:139], v[198:199], off offset:16
	global_load_dwordx4 v[202:205], v[198:199], off
	v_pk_mul_f32 v[120:121], v[120:121], v[148:149] op_sel_hi:[1,0]
	v_pk_mul_f32 v[124:125], v[124:125], v[148:149] op_sel_hi:[1,0]
	v_pk_mul_f32 v[198:199], v[186:187], v[120:121]
	v_pk_mul_f32 v[124:125], v[184:185], v[124:125]
	v_pk_mul_f32 v[122:123], v[122:123], v[148:149] op_sel_hi:[1,0]
	v_pk_mul_f32 v[126:127], v[126:127], v[148:149] op_sel_hi:[1,0]
	v_pk_mul_f32 v[112:113], v[112:113], v[148:149] op_sel_hi:[1,0]
	v_pk_mul_f32 v[126:127], v[188:189], v[126:127]
	v_pk_mul_f32 v[116:117], v[116:117], v[148:149] op_sel_hi:[1,0]
	v_pk_mul_f32 v[114:115], v[114:115], v[148:149] op_sel_hi:[1,0]
	v_pk_mul_f32 v[116:117], v[192:193], v[116:117]
	v_pk_mul_f32 v[118:119], v[118:119], v[148:149] op_sel_hi:[1,0]
	s_andn2_b64 vcc, exec, s[84:85]
	v_pk_mul_f32 v[118:119], v[196:197], v[118:119]
	s_waitcnt vmcnt(0)
	v_mov_b32_e32 v208, v202
	v_mov_b32_e32 v209, v204
	v_mov_b32_e32 v204, v203
	v_pk_mul_f32 v[120:121], v[204:205], v[198:199]
	v_pk_mul_f32 v[198:199], v[208:209], v[198:199]
	v_pk_fma_f32 v[120:121], v[208:209], v[124:125], v[120:121] neg_lo:[0,0,1] neg_hi:[0,0,1]
	v_pk_fma_f32 v[124:125], v[204:205], v[124:125], v[198:199]
	v_pk_mul_f32 v[198:199], v[190:191], v[122:123]
	v_mov_b32_e32 v202, v136
	v_mov_b32_e32 v203, v138
	v_mov_b32_e32 v138, v137
	v_pk_mul_f32 v[122:123], v[138:139], v[198:199]
	v_pk_mul_f32 v[136:137], v[202:203], v[198:199]
	v_pk_fma_f32 v[122:123], v[202:203], v[126:127], v[122:123] neg_lo:[0,0,1] neg_hi:[0,0,1]
	v_pk_fma_f32 v[126:127], v[138:139], v[126:127], v[136:137]
	v_pk_mul_f32 v[136:137], v[194:195], v[112:113]
	v_mov_b32_e32 v138, v132
	v_mov_b32_e32 v139, v134
	v_mov_b32_e32 v134, v133
	v_pk_mul_f32 v[112:113], v[134:135], v[136:137]
	v_pk_mul_f32 v[132:133], v[138:139], v[136:137]
	v_pk_fma_f32 v[112:113], v[138:139], v[116:117], v[112:113] neg_lo:[0,0,1] neg_hi:[0,0,1]
	v_pk_fma_f32 v[116:117], v[134:135], v[116:117], v[132:133]
	v_pk_mul_f32 v[132:133], v[182:183], v[114:115]
	v_mov_b32_e32 v135, v130
	v_mov_b32_e32 v130, v129
	v_mov_b32_e32 v134, v128
	v_pk_mul_f32 v[114:115], v[130:131], v[132:133]
	v_pk_mul_f32 v[128:129], v[134:135], v[132:133]
	v_pk_fma_f32 v[114:115], v[134:135], v[118:119], v[114:115] neg_lo:[0,0,1] neg_hi:[0,0,1]
	v_lshlrev_b64 v[136:137], 7, v[168:169]
	v_pk_fma_f32 v[118:119], v[130:131], v[118:119], v[128:129]
	v_cvt_pk_bf16_f32 v128, v120, v121
	v_cvt_pk_bf16_f32 v129, v122, v123
	v_cvt_pk_bf16_f32 v130, v112, v113
	v_cvt_pk_bf16_f32 v131, v114, v115
	v_lshl_add_u64 v[136:137], v[178:179], 0, v[136:137]
	v_cvt_pk_bf16_f32 v132, v124, v125
	v_cvt_pk_bf16_f32 v133, v126, v127
	v_cvt_pk_bf16_f32 v134, v116, v117
	v_cvt_pk_bf16_f32 v135, v118, v119
	v_lshl_add_u64 v[226:227], v[136:137], 0, v[220:221]
	v_lshl_add_u64 v[228:229], v[226:227], 0, s[90:91]
	global_store_dwordx4 v[226:227], v[128:131], off
	global_store_dwordx4 v[228:229], v[132:135], off
	s_nop 0
	v_cndmask_b32_e64 v128, 0, 1, s[84:85]
	v_cmp_ne_u32_e64 s[6:7], 1, v128
	s_cbranch_vccnz .LBB0_425
	v_pk_add_f32 v[202:203], v[120:121], 0 op_sel_hi:[1,0]
	v_pk_add_f32 v[198:199], v[124:125], 0 op_sel_hi:[1,0]
	v_pk_add_f32 v[138:139], v[122:123], 0 op_sel_hi:[1,0]
	v_pk_add_f32 v[136:137], v[126:127], 0 op_sel_hi:[1,0]
	v_pk_add_f32 v[134:135], v[112:113], 0 op_sel_hi:[1,0]
	v_pk_add_f32 v[132:133], v[116:117], 0 op_sel_hi:[1,0]
	v_pk_add_f32 v[130:131], v[114:115], 0 op_sel_hi:[1,0]
	v_pk_add_f32 v[128:129], v[118:119], 0 op_sel_hi:[1,0]
	s_branch .LBB0_426

; DI unsigned cvt_pk(float lo, float hi) { const f32x2 v = {lo, hi}; return __builtin_bit_cast(unsigned, __builtin_convertvector(v, bf16v2)); }
;     __device__ __forceinline__ void operator()(const f32x4 (&acc)[2][2][4][2], const Unit& u, int wr, int wc, int fr, int fq) const {
;     ...
;                 for (int m = 0; m < 4; ++m) {
;                     const int s = sbase + ai * 128 + m * 16; const float r = ROW_RS(ai, m);
;                     float t0[8], t1[8]; float ss = 0.f;
; #pragma unroll
;                     for (int n = 0; n < 2; ++n)
; #pragma unroll
;                         for (int j = 0; j < 4; ++j) { t0[4 * n + j] = acc[ai][0][m][n][j]; t1[4 * n + j] = acc[ai][1][m][n][j]; }
; #pragma unroll
;                     for (int i = 0; i < 8; ++i) ss += t0[i] * t0[i] + t1[i] * t1[i];
;                     ss += __shfl_xor(ss, 16); ss += __shfl_xor(ss, 32);
;                     const float hr = r * rsqrtf(ss * (r * r) * (1.0f / 64.0f) + NORM_EPS);
;                     const f32x4* cp = (const f32x4*)(cs + (size_t)s * 32 + 8 * fq);
;                     float o0[8], o1[8];
; #pragma unroll
;                     for (int q = 0; q < 4; ++q) { const f32x4 c4 = cp[q];
;                         { const int i = 2 * q; const float a = t0[i] * hr * g0[i], bb = t1[i] * hr * g1[i]; o0[i] = a * c4[0] - bb * c4[1]; o1[i] = bb * c4[0] + a * c4[1]; }
;                         { const int i = 2 * q + 1; const float a = t0[i] * hr * g0[i], bb = t1[i] * hr * g1[i]; o0[i] = a * c4[2] - bb * c4[3]; o1[i] = bb * c4[2] + a * c4[3]; } }
;                     u32x4 w0, w1;
;                     w0.x = cvt_pk(o0[0], o0[1]); w0.y = cvt_pk(o0[2], o0[3]); w0.z = cvt_pk(o0[4], o0[5]); w0.w = cvt_pk(o0[6], o0[7]);
;                     w1.x = cvt_pk(o1[0], o1[1]); w1.y = cvt_pk(o1[2], o1[3]); w1.z = cvt_pk(o1[4], o1[5]); w1.w = cvt_pk(o1[6], o1[7]);
;                     bf16_t* rp = dst + ((bh * SEQ + s) * 64 + 8 * fq);
;                     *(u32x4*)rp = w0; *(u32x4*)(rp + 32) = w1;
;                     if (do_km) {
; #pragma unroll
;                         for (int i = 0; i < 8; ++i) { cs0[i] += o0[i]; cs1[i] += o1[i]; }
;                     }
.LBB0_426:
	v_or_b32_e32 v204, 16, v168
	v_ashrrev_i32_e32 v205, 31, v204
	v_lshlrev_b64 v[112:113], 8, v[204:205]
	v_lshl_add_u64 v[112:113], v[152:153], 0, v[112:113]
	global_load_dwordx4 v[124:127], v[112:113], off
	global_load_dwordx4 v[120:123], v[112:113], off offset:16
	global_load_dwordx4 v[116:119], v[112:113], off offset:32
	s_nop 0
	global_load_dwordx4 v[112:115], v[112:113], off offset:48
	v_pk_mul_f32 v[210:211], v[104:105], v[104:105]
	v_pk_mul_f32 v[208:209], v[106:107], v[106:107]
	v_pk_fma_f32 v[210:211], v[108:109], v[108:109], v[210:211]
	v_pk_fma_f32 v[208:209], v[110:111], v[110:111], v[208:209]
	v_add_f32_e32 v148, v210, v211
	v_pk_mul_f32 v[214:215], v[96:97], v[96:97]
	v_add_f32_e32 v148, v208, v148
	v_pk_fma_f32 v[214:215], v[100:101], v[100:101], v[214:215]
	v_add_f32_e32 v148, v209, v148
	v_pk_mul_f32 v[212:213], v[98:99], v[98:99]
	v_add_f32_e32 v148, v214, v148
	v_pk_fma_f32 v[212:213], v[102:103], v[102:103], v[212:213]
	v_add_f32_e32 v148, v215, v148
	v_add_f32_e32 v148, v212, v148
	v_add_f32_e32 v148, v213, v148
	ds_bpermute_b32 v169, v206, v148
	v_mul_f32_e32 v208, v200, v200
	s_waitcnt lgkmcnt(0)
	v_add_f32_e32 v148, v148, v169
	ds_bpermute_b32 v169, v207, v148
	s_waitcnt lgkmcnt(0)
	v_add_f32_e32 v148, v148, v169
	v_mul_f32_e32 v148, v208, v148
	v_fmamk_f32 v148, v148, 0x3c800000, v177
	v_mul_f32_e32 v169, 0x4b800000, v148
	v_cmp_gt_f32_e32 vcc, s23, v148
	s_nop 1
	v_cndmask_b32_e32 v148, v148, v169, vcc
	v_rsq_f32_e32 v148, v148
	s_nop 0
	v_mul_f32_e32 v169, 0x45800000, v148
	v_cndmask_b32_e32 v148, v148, v169, vcc
	v_mul_f32_e32 v148, v200, v148
	v_pk_mul_f32 v[104:105], v[104:105], v[148:149] op_sel_hi:[1,0]
	v_pk_mul_f32 v[106:107], v[106:107], v[148:149] op_sel_hi:[1,0]
	v_pk_mul_f32 v[100:101], v[100:101], v[148:149] op_sel_hi:[1,0]
	v_pk_mul_f32 v[96:97], v[96:97], v[148:149] op_sel_hi:[1,0]
	v_pk_mul_f32 v[102:103], v[102:103], v[148:149] op_sel_hi:[1,0]
	v_pk_mul_f32 v[98:99], v[98:99], v[148:149] op_sel_hi:[1,0]
	v_pk_mul_f32 v[108:109], v[108:109], v[148:149] op_sel_hi:[1,0]
	v_pk_mul_f32 v[110:111], v[110:111], v[148:149] op_sel_hi:[1,0]
	v_pk_mul_f32 v[104:105], v[186:187], v[104:105]
	v_pk_mul_f32 v[106:107], v[190:191], v[106:107]
	v_pk_mul_f32 v[208:209], v[192:193], v[100:101]
	v_pk_mul_f32 v[96:97], v[194:195], v[96:97]
	v_pk_mul_f32 v[210:211], v[196:197], v[102:103]
	v_pk_mul_f32 v[98:99], v[182:183], v[98:99]
	v_pk_mul_f32 v[108:109], v[184:185], v[108:109]
	v_pk_mul_f32 v[110:111], v[188:189], v[110:111]
	s_and_b64 vcc, exec, s[6:7]
	s_waitcnt vmcnt(3)
	v_mov_b32_e32 v100, v124
	v_mov_b32_e32 v101, v126
	v_mov_b32_e32 v126, v125
	s_waitcnt vmcnt(2)
	v_mov_b32_e32 v102, v120
	v_mov_b32_e32 v103, v122
	v_mov_b32_e32 v122, v121
	s_waitcnt vmcnt(1)
	v_mov_b32_e32 v120, v116
	v_mov_b32_e32 v121, v118
	v_mov_b32_e32 v118, v117
	s_waitcnt vmcnt(0)
	v_mov_b32_e32 v116, v112
	v_mov_b32_e32 v117, v114
	v_mov_b32_e32 v114, v113
	v_pk_mul_f32 v[112:113], v[100:101], v[104:105]
	v_pk_mul_f32 v[104:105], v[126:127], v[104:105]
	v_pk_mul_f32 v[124:125], v[102:103], v[106:107]
	v_pk_mul_f32 v[106:107], v[122:123], v[106:107]
	v_pk_mul_f32 v[212:213], v[120:121], v[96:97]
	v_pk_mul_f32 v[214:215], v[118:119], v[96:97]
	v_pk_mul_f32 v[216:217], v[116:117], v[98:99]
	v_pk_mul_f32 v[218:219], v[114:115], v[98:99]
	v_pk_fma_f32 v[96:97], v[126:127], v[108:109], v[112:113]
	v_pk_fma_f32 v[104:105], v[100:101], v[108:109], v[104:105] neg_lo:[0,0,1] neg_hi:[0,0,1]
	v_pk_fma_f32 v[98:99], v[122:123], v[110:111], v[124:125]
	v_pk_fma_f32 v[106:107], v[102:103], v[110:111], v[106:107] neg_lo:[0,0,1] neg_hi:[0,0,1]
	v_pk_fma_f32 v[100:101], v[118:119], v[208:209], v[212:213]
	v_pk_fma_f32 v[108:109], v[120:121], v[208:209], v[214:215] neg_lo:[0,0,1] neg_hi:[0,0,1]
	v_pk_fma_f32 v[102:103], v[114:115], v[210:211], v[216:217]
	v_pk_fma_f32 v[110:111], v[116:117], v[210:211], v[218:219] neg_lo:[0,0,1] neg_hi:[0,0,1]
	v_lshlrev_b64 v[120:121], 7, v[204:205]
	v_cvt_pk_bf16_f32 v112, v104, v105
	v_cvt_pk_bf16_f32 v113, v106, v107
	v_cvt_pk_bf16_f32 v114, v108, v109
	v_cvt_pk_bf16_f32 v115, v110, v111
	v_cvt_pk_bf16_f32 v116, v96, v97
	v_cvt_pk_bf16_f32 v117, v98, v99
	v_cvt_pk_bf16_f32 v118, v100, v101
	v_cvt_pk_bf16_f32 v119, v102, v103
	v_lshl_add_u64 v[120:121], v[178:179], 0, v[120:121]
	v_lshl_add_u64 v[226:227], v[120:121], 0, v[222:223]
	v_lshl_add_u64 v[228:229], v[226:227], 0, s[90:91]
	global_store_dwordx4 v[226:227], v[112:115], off
	global_store_dwordx4 v[228:229], v[116:119], off
	s_cbranch_vccnz .LBB0_428
	v_pk_add_f32 v[202:203], v[202:203], v[104:105]
	v_pk_add_f32 v[198:199], v[198:199], v[96:97]
	v_pk_add_f32 v[138:139], v[138:139], v[106:107]
	v_pk_add_f32 v[136:137], v[136:137], v[98:99]
	v_pk_add_f32 v[134:135], v[134:135], v[108:109]
	v_pk_add_f32 v[132:133], v[132:133], v[100:101]
	v_pk_add_f32 v[130:131], v[130:131], v[110:111]
	v_pk_add_f32 v[128:129], v[128:129], v[102:103]
; DI unsigned cvt_pk(float lo, float hi) { const f32x2 v = {lo, hi}; return __builtin_bit_cast(unsigned, __builtin_convertvector(v, bf16v2)); }
;     __device__ __forceinline__ void operator()(const f32x4 (&acc)[2][2][4][2], const Unit& u, int wr, int wc, int fr, int fq) const {
;     ...
;                 for (int m = 0; m < 4; ++m) {
;                     const int s = sbase + ai * 128 + m * 16; const float r = ROW_RS(ai, m);
;                     float t0[8], t1[8]; float ss = 0.f;
; #pragma unroll
;                     for (int n = 0; n < 2; ++n)
; #pragma unroll
;                         for (int j = 0; j < 4; ++j) { t0[4 * n + j] = acc[ai][0][m][n][j]; t1[4 * n + j] = acc[ai][1][m][n][j]; }
; #pragma unroll
;                     for (int i = 0; i < 8; ++i) ss += t0[i] * t0[i] + t1[i] * t1[i];
;                     ss += __shfl_xor(ss, 16); ss += __shfl_xor(ss, 32);
;                     const float hr = r * rsqrtf(ss * (r * r) * (1.0f / 64.0f) + NORM_EPS);
;                     const f32x4* cp = (const f32x4*)(cs + (size_t)s * 32 + 8 * fq);
;                     float o0[8], o1[8];
; #pragma unroll
;                     for (int q = 0; q < 4; ++q) { const f32x4 c4 = cp[q];
;                         { const int i = 2 * q; const float a = t0[i] * hr * g0[i], bb = t1[i] * hr * g1[i]; o0[i] = a * c4[0] - bb * c4[1]; o1[i] = bb * c4[0] + a * c4[1]; }
;                         { const int i = 2 * q + 1; const float a = t0[i] * hr * g0[i], bb = t1[i] * hr * g1[i]; o0[i] = a * c4[2] - bb * c4[3]; o1[i] = bb * c4[2] + a * c4[3]; } }
;                     u32x4 w0, w1;
;                     w0.x = cvt_pk(o0[0], o0[1]); w0.y = cvt_pk(o0[2], o0[3]); w0.z = cvt_pk(o0[4], o0[5]); w0.w = cvt_pk(o0[6], o0[7]);
;                     w1.x = cvt_pk(o1[0], o1[1]); w1.y = cvt_pk(o1[2], o1[3]); w1.z = cvt_pk(o1[4], o1[5]); w1.w = cvt_pk(o1[6], o1[7]);
;                     bf16_t* rp = dst + ((bh * SEQ + s) * 64 + 8 * fq);
;                     *(u32x4*)rp = w0; *(u32x4*)(rp + 32) = w1;
;                     if (do_km) {
; #pragma unroll
;                         for (int i = 0; i < 8; ++i) { cs0[i] += o0[i]; cs1[i] += o1[i]; }
;                     }
.LBB0_428:
	v_or_b32_e32 v112, 32, v168
	v_ashrrev_i32_e32 v113, 31, v112
	v_lshlrev_b64 v[96:97], 8, v[112:113]
	v_lshl_add_u64 v[96:97], v[152:153], 0, v[96:97]
	global_load_dwordx4 v[108:111], v[96:97], off
	global_load_dwordx4 v[104:107], v[96:97], off offset:16
	global_load_dwordx4 v[100:103], v[96:97], off offset:32
	s_nop 0
	global_load_dwordx4 v[96:99], v[96:97], off offset:48
	v_pk_mul_f32 v[116:117], v[88:89], v[88:89]
	v_pk_mul_f32 v[114:115], v[90:91], v[90:91]
	v_pk_fma_f32 v[116:117], v[92:93], v[92:93], v[116:117]
	v_pk_fma_f32 v[114:115], v[94:95], v[94:95], v[114:115]
	v_add_f32_e32 v116, v116, v117
	v_pk_mul_f32 v[120:121], v[80:81], v[80:81]
	v_add_f32_e32 v114, v114, v116
	v_pk_fma_f32 v[120:121], v[84:85], v[84:85], v[120:121]
	v_add_f32_e32 v114, v115, v114
	v_pk_mul_f32 v[118:119], v[82:83], v[82:83]
	v_add_f32_e32 v114, v120, v114
	v_pk_fma_f32 v[118:119], v[86:87], v[86:87], v[118:119]
	v_add_f32_e32 v114, v121, v114
	v_add_f32_e32 v114, v118, v114
	v_add_f32_e32 v114, v119, v114
	ds_bpermute_b32 v115, v206, v114
	v_mul_f32_e32 v116, v180, v180
	s_waitcnt lgkmcnt(0)
	v_add_f32_e32 v114, v114, v115
	ds_bpermute_b32 v115, v207, v114
	s_waitcnt lgkmcnt(0)
	v_add_f32_e32 v114, v114, v115
	v_mul_f32_e32 v114, v116, v114
	v_fmamk_f32 v114, v114, 0x3c800000, v177
	v_mul_f32_e32 v115, 0x4b800000, v114
	v_cmp_gt_f32_e32 vcc, s23, v114
	s_nop 1
	v_cndmask_b32_e32 v114, v114, v115, vcc
	v_rsq_f32_e32 v114, v114
	s_nop 0
	v_mul_f32_e32 v115, 0x45800000, v114
	v_cndmask_b32_e32 v114, v114, v115, vcc
	v_mul_f32_e32 v114, v180, v114
	v_pk_mul_f32 v[88:89], v[88:89], v[114:115] op_sel_hi:[1,0]
	v_pk_mul_f32 v[90:91], v[90:91], v[114:115] op_sel_hi:[1,0]
	v_pk_mul_f32 v[84:85], v[84:85], v[114:115] op_sel_hi:[1,0]
	v_pk_mul_f32 v[80:81], v[80:81], v[114:115] op_sel_hi:[1,0]
	v_pk_mul_f32 v[86:87], v[86:87], v[114:115] op_sel_hi:[1,0]
	v_pk_mul_f32 v[82:83], v[82:83], v[114:115] op_sel_hi:[1,0]
	v_pk_mul_f32 v[92:93], v[92:93], v[114:115] op_sel_hi:[1,0]
	v_pk_mul_f32 v[94:95], v[94:95], v[114:115] op_sel_hi:[1,0]
	v_pk_mul_f32 v[88:89], v[186:187], v[88:89]
	v_pk_mul_f32 v[90:91], v[190:191], v[90:91]
	v_pk_mul_f32 v[114:115], v[192:193], v[84:85]
	v_pk_mul_f32 v[80:81], v[194:195], v[80:81]
	v_pk_mul_f32 v[116:117], v[196:197], v[86:87]
	v_pk_mul_f32 v[82:83], v[182:183], v[82:83]
	v_pk_mul_f32 v[92:93], v[184:185], v[92:93]
	v_pk_mul_f32 v[94:95], v[188:189], v[94:95]
	s_and_b64 vcc, exec, s[6:7]
	s_waitcnt vmcnt(3)
	v_mov_b32_e32 v84, v108
	v_mov_b32_e32 v85, v110
	v_mov_b32_e32 v110, v109
	s_waitcnt vmcnt(2)
	v_mov_b32_e32 v86, v104
	v_mov_b32_e32 v87, v106
	v_mov_b32_e32 v106, v105
	s_waitcnt vmcnt(1)
	v_mov_b32_e32 v104, v100
	v_mov_b32_e32 v105, v102
	v_mov_b32_e32 v102, v101
	s_waitcnt vmcnt(0)
	v_mov_b32_e32 v100, v96
	v_mov_b32_e32 v101, v98
	v_mov_b32_e32 v98, v97
	v_pk_mul_f32 v[96:97], v[84:85], v[88:89]
	v_pk_mul_f32 v[88:89], v[110:111], v[88:89]
	v_pk_mul_f32 v[108:109], v[86:87], v[90:91]
	v_pk_mul_f32 v[90:91], v[106:107], v[90:91]
	v_pk_mul_f32 v[118:119], v[104:105], v[80:81]
	v_pk_mul_f32 v[120:121], v[102:103], v[80:81]
	v_pk_mul_f32 v[122:123], v[100:101], v[82:83]
	v_pk_mul_f32 v[124:125], v[98:99], v[82:83]
	v_pk_fma_f32 v[80:81], v[110:111], v[92:93], v[96:97]
	v_pk_fma_f32 v[88:89], v[84:85], v[92:93], v[88:89] neg_lo:[0,0,1] neg_hi:[0,0,1]
	v_pk_fma_f32 v[82:83], v[106:107], v[94:95], v[108:109]
	v_pk_fma_f32 v[90:91], v[86:87], v[94:95], v[90:91] neg_lo:[0,0,1] neg_hi:[0,0,1]
	v_pk_fma_f32 v[84:85], v[102:103], v[114:115], v[118:119]
	v_pk_fma_f32 v[92:93], v[104:105], v[114:115], v[120:121] neg_lo:[0,0,1] neg_hi:[0,0,1]
	v_pk_fma_f32 v[86:87], v[98:99], v[116:117], v[122:123]
	v_pk_fma_f32 v[94:95], v[100:101], v[116:117], v[124:125] neg_lo:[0,0,1] neg_hi:[0,0,1]
	v_lshlrev_b64 v[104:105], 7, v[112:113]
	v_cvt_pk_bf16_f32 v96, v88, v89
	v_cvt_pk_bf16_f32 v97, v90, v91
	v_cvt_pk_bf16_f32 v98, v92, v93
	v_cvt_pk_bf16_f32 v99, v94, v95
	v_cvt_pk_bf16_f32 v100, v80, v81
	v_cvt_pk_bf16_f32 v101, v82, v83
	v_cvt_pk_bf16_f32 v102, v84, v85
	v_cvt_pk_bf16_f32 v103, v86, v87
	v_lshl_add_u64 v[104:105], v[178:179], 0, v[104:105]
	v_lshl_add_u64 v[226:227], v[104:105], 0, v[220:221]
	v_lshl_add_u64 v[228:229], v[226:227], 0, s[90:91]
	global_store_dwordx4 v[226:227], v[96:99], off
	global_store_dwordx4 v[228:229], v[100:103], off
	s_cbranch_vccnz .LBB0_430
	v_pk_add_f32 v[202:203], v[202:203], v[88:89]
	v_pk_add_f32 v[198:199], v[198:199], v[80:81]
	v_pk_add_f32 v[138:139], v[138:139], v[90:91]
	v_pk_add_f32 v[136:137], v[136:137], v[82:83]
	v_pk_add_f32 v[134:135], v[134:135], v[92:93]
	v_pk_add_f32 v[132:133], v[132:133], v[84:85]
	v_pk_add_f32 v[130:131], v[130:131], v[94:95]
	v_pk_add_f32 v[128:129], v[128:129], v[86:87]
; DI unsigned cvt_pk(float lo, float hi) { const f32x2 v = {lo, hi}; return __builtin_bit_cast(unsigned, __builtin_convertvector(v, bf16v2)); }
;     __device__ __forceinline__ void operator()(const f32x4 (&acc)[2][2][4][2], const Unit& u, int wr, int wc, int fr, int fq) const {
;     ...
;                 for (int m = 0; m < 4; ++m) {
;                     const int s = sbase + ai * 128 + m * 16; const float r = ROW_RS(ai, m);
;                     float t0[8], t1[8]; float ss = 0.f;
; #pragma unroll
;                     for (int n = 0; n < 2; ++n)
; #pragma unroll
;                         for (int j = 0; j < 4; ++j) { t0[4 * n + j] = acc[ai][0][m][n][j]; t1[4 * n + j] = acc[ai][1][m][n][j]; }
; #pragma unroll
;                     for (int i = 0; i < 8; ++i) ss += t0[i] * t0[i] + t1[i] * t1[i];
;                     ss += __shfl_xor(ss, 16); ss += __shfl_xor(ss, 32);
;                     const float hr = r * rsqrtf(ss * (r * r) * (1.0f / 64.0f) + NORM_EPS);
;                     const f32x4* cp = (const f32x4*)(cs + (size_t)s * 32 + 8 * fq);
;                     float o0[8], o1[8];
; #pragma unroll
;                     for (int q = 0; q < 4; ++q) { const f32x4 c4 = cp[q];
;                         { const int i = 2 * q; const float a = t0[i] * hr * g0[i], bb = t1[i] * hr * g1[i]; o0[i] = a * c4[0] - bb * c4[1]; o1[i] = bb * c4[0] + a * c4[1]; }
;                         { const int i = 2 * q + 1; const float a = t0[i] * hr * g0[i], bb = t1[i] * hr * g1[i]; o0[i] = a * c4[2] - bb * c4[3]; o1[i] = bb * c4[2] + a * c4[3]; } }
;                     u32x4 w0, w1;
;                     w0.x = cvt_pk(o0[0], o0[1]); w0.y = cvt_pk(o0[2], o0[3]); w0.z = cvt_pk(o0[4], o0[5]); w0.w = cvt_pk(o0[6], o0[7]);
;                     w1.x = cvt_pk(o1[0], o1[1]); w1.y = cvt_pk(o1[2], o1[3]); w1.z = cvt_pk(o1[4], o1[5]); w1.w = cvt_pk(o1[6], o1[7]);
;                     bf16_t* rp = dst + ((bh * SEQ + s) * 64 + 8 * fq);
;                     *(u32x4*)rp = w0; *(u32x4*)(rp + 32) = w1;
;                     if (do_km) {
; #pragma unroll
;                         for (int i = 0; i < 8; ++i) { cs0[i] += o0[i]; cs1[i] += o1[i]; }
;                     }
.LBB0_430:
	v_or_b32_e32 v96, 48, v168
	v_ashrrev_i32_e32 v97, 31, v96
	v_lshlrev_b64 v[80:81], 8, v[96:97]
	v_lshl_add_u64 v[80:81], v[152:153], 0, v[80:81]
	global_load_dwordx4 v[92:95], v[80:81], off
	global_load_dwordx4 v[88:91], v[80:81], off offset:16
	global_load_dwordx4 v[84:87], v[80:81], off offset:32
	s_nop 0
	global_load_dwordx4 v[80:83], v[80:81], off offset:48
	v_pk_mul_f32 v[100:101], v[72:73], v[72:73]
	v_pk_mul_f32 v[98:99], v[74:75], v[74:75]
	v_pk_fma_f32 v[100:101], v[76:77], v[76:77], v[100:101]
	v_pk_fma_f32 v[98:99], v[78:79], v[78:79], v[98:99]
	v_add_f32_e32 v100, v100, v101
	v_pk_mul_f32 v[104:105], v[64:65], v[64:65]
	v_add_f32_e32 v98, v98, v100
	v_pk_fma_f32 v[104:105], v[68:69], v[68:69], v[104:105]
	v_add_f32_e32 v98, v99, v98
	v_pk_mul_f32 v[102:103], v[66:67], v[66:67]
	v_add_f32_e32 v98, v104, v98
	v_pk_fma_f32 v[102:103], v[70:71], v[70:71], v[102:103]
	v_add_f32_e32 v98, v105, v98
	v_add_f32_e32 v98, v102, v98
	v_add_f32_e32 v98, v103, v98
	ds_bpermute_b32 v99, v206, v98
	v_mul_f32_e32 v100, v176, v176
	s_waitcnt lgkmcnt(0)
	v_add_f32_e32 v98, v98, v99
	ds_bpermute_b32 v99, v207, v98
	s_waitcnt lgkmcnt(0)
	v_add_f32_e32 v98, v98, v99
	v_mul_f32_e32 v98, v100, v98
	v_fmamk_f32 v98, v98, 0x3c800000, v177
	v_mul_f32_e32 v99, 0x4b800000, v98
	v_cmp_gt_f32_e32 vcc, s23, v98
	s_nop 1
	v_cndmask_b32_e32 v98, v98, v99, vcc
	v_rsq_f32_e32 v98, v98
	s_nop 0
	v_mul_f32_e32 v99, 0x45800000, v98
	v_cndmask_b32_e32 v98, v98, v99, vcc
	v_mul_f32_e32 v98, v176, v98
	v_pk_mul_f32 v[72:73], v[72:73], v[98:99] op_sel_hi:[1,0]
	v_pk_mul_f32 v[74:75], v[74:75], v[98:99] op_sel_hi:[1,0]
	v_pk_mul_f32 v[68:69], v[68:69], v[98:99] op_sel_hi:[1,0]
	v_pk_mul_f32 v[64:65], v[64:65], v[98:99] op_sel_hi:[1,0]
	v_pk_mul_f32 v[70:71], v[70:71], v[98:99] op_sel_hi:[1,0]
	v_pk_mul_f32 v[66:67], v[66:67], v[98:99] op_sel_hi:[1,0]
	v_pk_mul_f32 v[76:77], v[76:77], v[98:99] op_sel_hi:[1,0]
	v_pk_mul_f32 v[78:79], v[78:79], v[98:99] op_sel_hi:[1,0]
	v_pk_mul_f32 v[72:73], v[186:187], v[72:73]
	v_pk_mul_f32 v[74:75], v[190:191], v[74:75]
	v_pk_mul_f32 v[98:99], v[192:193], v[68:69]
	v_pk_mul_f32 v[64:65], v[194:195], v[64:65]
	v_pk_mul_f32 v[100:101], v[196:197], v[70:71]
	v_pk_mul_f32 v[66:67], v[182:183], v[66:67]
	v_pk_mul_f32 v[76:77], v[184:185], v[76:77]
	v_pk_mul_f32 v[78:79], v[188:189], v[78:79]
	s_and_b64 vcc, exec, s[6:7]
	s_waitcnt vmcnt(3)
	v_mov_b32_e32 v68, v92
	v_mov_b32_e32 v69, v94
	v_mov_b32_e32 v94, v93
	s_waitcnt vmcnt(2)
	v_mov_b32_e32 v70, v88
	v_mov_b32_e32 v71, v90
	v_mov_b32_e32 v90, v89
	s_waitcnt vmcnt(1)
	v_mov_b32_e32 v88, v84
	v_mov_b32_e32 v89, v86
	v_mov_b32_e32 v86, v85
	s_waitcnt vmcnt(0)
	v_mov_b32_e32 v84, v80
	v_mov_b32_e32 v85, v82
	v_mov_b32_e32 v82, v81
	v_pk_mul_f32 v[80:81], v[68:69], v[72:73]
	v_pk_mul_f32 v[72:73], v[94:95], v[72:73]
	v_pk_mul_f32 v[92:93], v[70:71], v[74:75]
	v_pk_mul_f32 v[74:75], v[90:91], v[74:75]
	v_pk_mul_f32 v[102:103], v[88:89], v[64:65]
	v_pk_mul_f32 v[104:105], v[86:87], v[64:65]
	v_pk_mul_f32 v[106:107], v[84:85], v[66:67]
	v_pk_mul_f32 v[108:109], v[82:83], v[66:67]
	v_pk_fma_f32 v[64:65], v[94:95], v[76:77], v[80:81]
	v_pk_fma_f32 v[72:73], v[68:69], v[76:77], v[72:73] neg_lo:[0,0,1] neg_hi:[0,0,1]
	v_pk_fma_f32 v[66:67], v[90:91], v[78:79], v[92:93]
	v_pk_fma_f32 v[74:75], v[70:71], v[78:79], v[74:75] neg_lo:[0,0,1] neg_hi:[0,0,1]
	v_pk_fma_f32 v[68:69], v[86:87], v[98:99], v[102:103]
	v_pk_fma_f32 v[76:77], v[88:89], v[98:99], v[104:105] neg_lo:[0,0,1] neg_hi:[0,0,1]
	v_pk_fma_f32 v[70:71], v[82:83], v[100:101], v[106:107]
	v_pk_fma_f32 v[78:79], v[84:85], v[100:101], v[108:109] neg_lo:[0,0,1] neg_hi:[0,0,1]
	v_lshlrev_b64 v[88:89], 7, v[96:97]
	v_cvt_pk_bf16_f32 v80, v72, v73
	v_cvt_pk_bf16_f32 v81, v74, v75
	v_cvt_pk_bf16_f32 v82, v76, v77
	v_cvt_pk_bf16_f32 v83, v78, v79
	v_cvt_pk_bf16_f32 v84, v64, v65
	v_cvt_pk_bf16_f32 v85, v66, v67
	v_cvt_pk_bf16_f32 v86, v68, v69
	v_cvt_pk_bf16_f32 v87, v70, v71
	v_lshl_add_u64 v[88:89], v[178:179], 0, v[88:89]
	v_lshl_add_u64 v[226:227], v[88:89], 0, v[222:223]
	v_lshl_add_u64 v[228:229], v[226:227], 0, s[90:91]
	global_store_dwordx4 v[226:227], v[80:83], off
	global_store_dwordx4 v[228:229], v[84:87], off
	s_cbranch_vccnz .LBB0_432
	v_pk_add_f32 v[202:203], v[202:203], v[72:73]
	v_pk_add_f32 v[198:199], v[198:199], v[64:65]
	v_pk_add_f32 v[138:139], v[138:139], v[74:75]
	v_pk_add_f32 v[136:137], v[136:137], v[66:67]
	v_pk_add_f32 v[134:135], v[134:135], v[76:77]
	v_pk_add_f32 v[132:133], v[132:133], v[68:69]
	v_pk_add_f32 v[130:131], v[130:131], v[78:79]
	v_pk_add_f32 v[128:129], v[128:129], v[70:71]
; DI unsigned cvt_pk(float lo, float hi) { const f32x2 v = {lo, hi}; return __builtin_bit_cast(unsigned, __builtin_convertvector(v, bf16v2)); }
;     __device__ __forceinline__ void operator()(const f32x4 (&acc)[2][2][4][2], const Unit& u, int wr, int wc, int fr, int fq) const {
;     ...
;                 for (int m = 0; m < 4; ++m) {
;                     const int s = sbase + ai * 128 + m * 16; const float r = ROW_RS(ai, m);
;                     float t0[8], t1[8]; float ss = 0.f;
; #pragma unroll
;                     for (int n = 0; n < 2; ++n)
; #pragma unroll
;                         for (int j = 0; j < 4; ++j) { t0[4 * n + j] = acc[ai][0][m][n][j]; t1[4 * n + j] = acc[ai][1][m][n][j]; }
; #pragma unroll
;                     for (int i = 0; i < 8; ++i) ss += t0[i] * t0[i] + t1[i] * t1[i];
;                     ss += __shfl_xor(ss, 16); ss += __shfl_xor(ss, 32);
;                     const float hr = r * rsqrtf(ss * (r * r) * (1.0f / 64.0f) + NORM_EPS);
;                     const f32x4* cp = (const f32x4*)(cs + (size_t)s * 32 + 8 * fq);
;                     float o0[8], o1[8];
; #pragma unroll
;                     for (int q = 0; q < 4; ++q) { const f32x4 c4 = cp[q];
;                         { const int i = 2 * q; const float a = t0[i] * hr * g0[i], bb = t1[i] * hr * g1[i]; o0[i] = a * c4[0] - bb * c4[1]; o1[i] = bb * c4[0] + a * c4[1]; }
;                         { const int i = 2 * q + 1; const float a = t0[i] * hr * g0[i], bb = t1[i] * hr * g1[i]; o0[i] = a * c4[2] - bb * c4[3]; o1[i] = bb * c4[2] + a * c4[3]; } }
;                     u32x4 w0, w1;
;                     w0.x = cvt_pk(o0[0], o0[1]); w0.y = cvt_pk(o0[2], o0[3]); w0.z = cvt_pk(o0[4], o0[5]); w0.w = cvt_pk(o0[6], o0[7]);
;                     w1.x = cvt_pk(o1[0], o1[1]); w1.y = cvt_pk(o1[2], o1[3]); w1.z = cvt_pk(o1[4], o1[5]); w1.w = cvt_pk(o1[6], o1[7]);
;                     bf16_t* rp = dst + ((bh * SEQ + s) * 64 + 8 * fq);
;                     *(u32x4*)rp = w0; *(u32x4*)(rp + 32) = w1;
;                     if (do_km) {
; #pragma unroll
;                         for (int i = 0; i < 8; ++i) { cs0[i] += o0[i]; cs1[i] += o1[i]; }
;                     }
.LBB0_432:
	v_add_u32_e32 v80, 0x80, v168
	v_ashrrev_i32_e32 v81, 31, v80
	v_lshlrev_b64 v[64:65], 8, v[80:81]
	v_lshl_add_u64 v[64:65], v[152:153], 0, v[64:65]
	global_load_dwordx4 v[76:79], v[64:65], off
	global_load_dwordx4 v[72:75], v[64:65], off offset:16
	global_load_dwordx4 v[68:71], v[64:65], off offset:32
	s_nop 0
	global_load_dwordx4 v[64:67], v[64:65], off offset:48
	v_pk_mul_f32 v[84:85], v[56:57], v[56:57]
	v_pk_mul_f32 v[82:83], v[58:59], v[58:59]
	v_pk_fma_f32 v[84:85], v[60:61], v[60:61], v[84:85]
	v_pk_fma_f32 v[82:83], v[62:63], v[62:63], v[82:83]
	v_add_f32_e32 v84, v84, v85
	v_pk_mul_f32 v[88:89], v[48:49], v[48:49]
	v_add_f32_e32 v82, v82, v84
	v_pk_fma_f32 v[88:89], v[52:53], v[52:53], v[88:89]
	v_add_f32_e32 v82, v83, v82
	v_pk_mul_f32 v[86:87], v[50:51], v[50:51]
	v_add_f32_e32 v82, v88, v82
	v_pk_fma_f32 v[86:87], v[54:55], v[54:55], v[86:87]
	v_add_f32_e32 v82, v89, v82
	v_add_f32_e32 v82, v86, v82
	v_add_f32_e32 v82, v87, v82
	ds_bpermute_b32 v83, v206, v82
	v_mul_f32_e32 v84, v174, v174
	s_waitcnt lgkmcnt(0)
	v_add_f32_e32 v82, v82, v83
	ds_bpermute_b32 v83, v207, v82
	s_waitcnt lgkmcnt(0)
	v_add_f32_e32 v82, v82, v83
	v_mul_f32_e32 v82, v84, v82
	v_fmamk_f32 v82, v82, 0x3c800000, v177
	v_mul_f32_e32 v83, 0x4b800000, v82
	v_cmp_gt_f32_e32 vcc, s23, v82
	s_nop 1
	v_cndmask_b32_e32 v82, v82, v83, vcc
	v_rsq_f32_e32 v82, v82
	s_nop 0
	v_mul_f32_e32 v83, 0x45800000, v82
	v_cndmask_b32_e32 v82, v82, v83, vcc
	v_mul_f32_e32 v82, v174, v82
	v_pk_mul_f32 v[56:57], v[56:57], v[82:83] op_sel_hi:[1,0]
	v_pk_mul_f32 v[58:59], v[58:59], v[82:83] op_sel_hi:[1,0]
	v_pk_mul_f32 v[52:53], v[52:53], v[82:83] op_sel_hi:[1,0]
	v_pk_mul_f32 v[48:49], v[48:49], v[82:83] op_sel_hi:[1,0]
	v_pk_mul_f32 v[54:55], v[54:55], v[82:83] op_sel_hi:[1,0]
	v_pk_mul_f32 v[50:51], v[50:51], v[82:83] op_sel_hi:[1,0]
	v_pk_mul_f32 v[60:61], v[60:61], v[82:83] op_sel_hi:[1,0]
	v_pk_mul_f32 v[62:63], v[62:63], v[82:83] op_sel_hi:[1,0]
	v_pk_mul_f32 v[56:57], v[186:187], v[56:57]
	v_pk_mul_f32 v[58:59], v[190:191], v[58:59]
	v_pk_mul_f32 v[82:83], v[192:193], v[52:53]
	v_pk_mul_f32 v[48:49], v[194:195], v[48:49]
	v_pk_mul_f32 v[84:85], v[196:197], v[54:55]
	v_pk_mul_f32 v[50:51], v[182:183], v[50:51]
	v_pk_mul_f32 v[60:61], v[184:185], v[60:61]
	v_pk_mul_f32 v[62:63], v[188:189], v[62:63]
	s_and_b64 vcc, exec, s[6:7]
	s_waitcnt vmcnt(3)
	v_mov_b32_e32 v52, v76
	v_mov_b32_e32 v53, v78
	v_mov_b32_e32 v78, v77
	s_waitcnt vmcnt(2)
	v_mov_b32_e32 v54, v72
	v_mov_b32_e32 v55, v74
	v_mov_b32_e32 v74, v73
	s_waitcnt vmcnt(1)
	v_mov_b32_e32 v72, v68
	v_mov_b32_e32 v73, v70
	v_mov_b32_e32 v70, v69
	s_waitcnt vmcnt(0)
	v_mov_b32_e32 v68, v64
	v_mov_b32_e32 v69, v66
	v_mov_b32_e32 v66, v65
	v_pk_mul_f32 v[64:65], v[52:53], v[56:57]
	v_pk_mul_f32 v[56:57], v[78:79], v[56:57]
	v_pk_mul_f32 v[76:77], v[54:55], v[58:59]
	v_pk_mul_f32 v[58:59], v[74:75], v[58:59]
	v_pk_mul_f32 v[86:87], v[72:73], v[48:49]
	v_pk_mul_f32 v[88:89], v[70:71], v[48:49]
	v_pk_mul_f32 v[90:91], v[68:69], v[50:51]
	v_pk_mul_f32 v[92:93], v[66:67], v[50:51]
	v_pk_fma_f32 v[48:49], v[78:79], v[60:61], v[64:65]
	v_pk_fma_f32 v[56:57], v[52:53], v[60:61], v[56:57] neg_lo:[0,0,1] neg_hi:[0,0,1]
	v_pk_fma_f32 v[50:51], v[74:75], v[62:63], v[76:77]
	v_pk_fma_f32 v[58:59], v[54:55], v[62:63], v[58:59] neg_lo:[0,0,1] neg_hi:[0,0,1]
	v_pk_fma_f32 v[52:53], v[70:71], v[82:83], v[86:87]
	v_pk_fma_f32 v[60:61], v[72:73], v[82:83], v[88:89] neg_lo:[0,0,1] neg_hi:[0,0,1]
	v_pk_fma_f32 v[54:55], v[66:67], v[84:85], v[90:91]
	v_pk_fma_f32 v[62:63], v[68:69], v[84:85], v[92:93] neg_lo:[0,0,1] neg_hi:[0,0,1]
	v_lshlrev_b64 v[72:73], 7, v[80:81]
	v_cvt_pk_bf16_f32 v64, v56, v57
	v_cvt_pk_bf16_f32 v65, v58, v59
	v_cvt_pk_bf16_f32 v66, v60, v61
	v_cvt_pk_bf16_f32 v67, v62, v63
	v_cvt_pk_bf16_f32 v68, v48, v49
	v_cvt_pk_bf16_f32 v69, v50, v51
	v_cvt_pk_bf16_f32 v70, v52, v53
	v_cvt_pk_bf16_f32 v71, v54, v55
	v_lshl_add_u64 v[72:73], v[178:179], 0, v[72:73]
	v_lshl_add_u64 v[226:227], v[72:73], 0, v[220:221]
	v_lshl_add_u64 v[228:229], v[226:227], 0, s[90:91]
	global_store_dwordx4 v[226:227], v[64:67], off
	global_store_dwordx4 v[228:229], v[68:71], off
	s_cbranch_vccnz .LBB0_434
	v_pk_add_f32 v[202:203], v[202:203], v[56:57]
	v_pk_add_f32 v[198:199], v[198:199], v[48:49]
	v_pk_add_f32 v[138:139], v[138:139], v[58:59]
	v_pk_add_f32 v[136:137], v[136:137], v[50:51]
	v_pk_add_f32 v[134:135], v[134:135], v[60:61]
	v_pk_add_f32 v[132:133], v[132:133], v[52:53]
	v_pk_add_f32 v[130:131], v[130:131], v[62:63]
	v_pk_add_f32 v[128:129], v[128:129], v[54:55]
; DI unsigned cvt_pk(float lo, float hi) { const f32x2 v = {lo, hi}; return __builtin_bit_cast(unsigned, __builtin_convertvector(v, bf16v2)); }
;     __device__ __forceinline__ void operator()(const f32x4 (&acc)[2][2][4][2], const Unit& u, int wr, int wc, int fr, int fq) const {
;     ...
;                 for (int m = 0; m < 4; ++m) {
;                     const int s = sbase + ai * 128 + m * 16; const float r = ROW_RS(ai, m);
;                     float t0[8], t1[8]; float ss = 0.f;
; #pragma unroll
;                     for (int n = 0; n < 2; ++n)
; #pragma unroll
;                         for (int j = 0; j < 4; ++j) { t0[4 * n + j] = acc[ai][0][m][n][j]; t1[4 * n + j] = acc[ai][1][m][n][j]; }
; #pragma unroll
;                     for (int i = 0; i < 8; ++i) ss += t0[i] * t0[i] + t1[i] * t1[i];
;                     ss += __shfl_xor(ss, 16); ss += __shfl_xor(ss, 32);
;                     const float hr = r * rsqrtf(ss * (r * r) * (1.0f / 64.0f) + NORM_EPS);
;                     const f32x4* cp = (const f32x4*)(cs + (size_t)s * 32 + 8 * fq);
;                     float o0[8], o1[8];
; #pragma unroll
;                     for (int q = 0; q < 4; ++q) { const f32x4 c4 = cp[q];
;                         { const int i = 2 * q; const float a = t0[i] * hr * g0[i], bb = t1[i] * hr * g1[i]; o0[i] = a * c4[0] - bb * c4[1]; o1[i] = bb * c4[0] + a * c4[1]; }
;                         { const int i = 2 * q + 1; const float a = t0[i] * hr * g0[i], bb = t1[i] * hr * g1[i]; o0[i] = a * c4[2] - bb * c4[3]; o1[i] = bb * c4[2] + a * c4[3]; } }
;                     u32x4 w0, w1;
;                     w0.x = cvt_pk(o0[0], o0[1]); w0.y = cvt_pk(o0[2], o0[3]); w0.z = cvt_pk(o0[4], o0[5]); w0.w = cvt_pk(o0[6], o0[7]);
;                     w1.x = cvt_pk(o1[0], o1[1]); w1.y = cvt_pk(o1[2], o1[3]); w1.z = cvt_pk(o1[4], o1[5]); w1.w = cvt_pk(o1[6], o1[7]);
;                     bf16_t* rp = dst + ((bh * SEQ + s) * 64 + 8 * fq);
;                     *(u32x4*)rp = w0; *(u32x4*)(rp + 32) = w1;
;                     if (do_km) {
; #pragma unroll
;                         for (int i = 0; i < 8; ++i) { cs0[i] += o0[i]; cs1[i] += o1[i]; }
;                     }
.LBB0_434:
	v_add_u32_e32 v64, 0x90, v168
	v_ashrrev_i32_e32 v65, 31, v64
	v_lshlrev_b64 v[48:49], 8, v[64:65]
	v_lshl_add_u64 v[48:49], v[152:153], 0, v[48:49]
	global_load_dwordx4 v[60:63], v[48:49], off
	global_load_dwordx4 v[56:59], v[48:49], off offset:16
	global_load_dwordx4 v[52:55], v[48:49], off offset:32
	s_nop 0
	global_load_dwordx4 v[48:51], v[48:49], off offset:48
	v_pk_mul_f32 v[68:69], v[40:41], v[40:41]
	v_pk_mul_f32 v[66:67], v[42:43], v[42:43]
	v_pk_fma_f32 v[68:69], v[44:45], v[44:45], v[68:69]
	v_pk_fma_f32 v[66:67], v[46:47], v[46:47], v[66:67]
	v_add_f32_e32 v68, v68, v69
	v_pk_mul_f32 v[72:73], v[32:33], v[32:33]
	v_add_f32_e32 v66, v66, v68
	v_pk_fma_f32 v[72:73], v[36:37], v[36:37], v[72:73]
	v_add_f32_e32 v66, v67, v66
	v_pk_mul_f32 v[70:71], v[34:35], v[34:35]
	v_add_f32_e32 v66, v72, v66
	v_pk_fma_f32 v[70:71], v[38:39], v[38:39], v[70:71]
	v_add_f32_e32 v66, v73, v66
	v_add_f32_e32 v66, v70, v66
	v_add_f32_e32 v66, v71, v66
	ds_bpermute_b32 v67, v206, v66
	v_mul_f32_e32 v68, v172, v172
	s_waitcnt lgkmcnt(0)
	v_add_f32_e32 v66, v66, v67
	ds_bpermute_b32 v67, v207, v66
	s_waitcnt lgkmcnt(0)
	v_add_f32_e32 v66, v66, v67
	v_mul_f32_e32 v66, v68, v66
	v_fmamk_f32 v66, v66, 0x3c800000, v177
	v_mul_f32_e32 v67, 0x4b800000, v66
	v_cmp_gt_f32_e32 vcc, s23, v66
	s_nop 1
	v_cndmask_b32_e32 v66, v66, v67, vcc
	v_rsq_f32_e32 v66, v66
	s_nop 0
	v_mul_f32_e32 v67, 0x45800000, v66
	v_cndmask_b32_e32 v66, v66, v67, vcc
	v_mul_f32_e32 v66, v172, v66
	v_pk_mul_f32 v[40:41], v[40:41], v[66:67] op_sel_hi:[1,0]
	v_pk_mul_f32 v[42:43], v[42:43], v[66:67] op_sel_hi:[1,0]
	v_pk_mul_f32 v[32:33], v[32:33], v[66:67] op_sel_hi:[1,0]
	v_pk_mul_f32 v[36:37], v[36:37], v[66:67] op_sel_hi:[1,0]
	v_pk_mul_f32 v[34:35], v[34:35], v[66:67] op_sel_hi:[1,0]
	v_pk_mul_f32 v[38:39], v[38:39], v[66:67] op_sel_hi:[1,0]
	v_pk_mul_f32 v[44:45], v[44:45], v[66:67] op_sel_hi:[1,0]
	v_pk_mul_f32 v[46:47], v[46:47], v[66:67] op_sel_hi:[1,0]
	v_pk_mul_f32 v[40:41], v[186:187], v[40:41]
	v_pk_mul_f32 v[42:43], v[190:191], v[42:43]
	v_pk_mul_f32 v[32:33], v[194:195], v[32:33]
	v_pk_mul_f32 v[66:67], v[192:193], v[36:37]
	v_pk_mul_f32 v[34:35], v[182:183], v[34:35]
	v_pk_mul_f32 v[68:69], v[196:197], v[38:39]
	v_pk_mul_f32 v[44:45], v[184:185], v[44:45]
	v_pk_mul_f32 v[46:47], v[188:189], v[46:47]
	s_and_b64 vcc, exec, s[6:7]
	s_waitcnt vmcnt(3)
	v_mov_b32_e32 v36, v61
	v_mov_b32_e32 v37, v63
	v_mov_b32_e32 v61, v62
	s_waitcnt vmcnt(2)
	v_mov_b32_e32 v38, v57
	v_mov_b32_e32 v39, v59
	v_mov_b32_e32 v57, v58
	s_waitcnt vmcnt(1)
	v_mov_b32_e32 v58, v53
	v_mov_b32_e32 v59, v55
	v_mov_b32_e32 v53, v54
	s_waitcnt vmcnt(0)
	v_mov_b32_e32 v54, v49
	v_mov_b32_e32 v55, v51
	v_mov_b32_e32 v49, v50
	v_pk_mul_f32 v[50:51], v[36:37], v[40:41]
	v_pk_mul_f32 v[40:41], v[60:61], v[40:41]
	v_pk_mul_f32 v[62:63], v[38:39], v[42:43]
	v_pk_mul_f32 v[42:43], v[56:57], v[42:43]
	v_pk_mul_f32 v[70:71], v[58:59], v[32:33]
	v_pk_mul_f32 v[72:73], v[52:53], v[32:33]
	v_pk_mul_f32 v[74:75], v[54:55], v[34:35]
	v_pk_mul_f32 v[76:77], v[48:49], v[34:35]
	v_pk_fma_f32 v[32:33], v[60:61], v[44:45], v[50:51] neg_lo:[0,0,1] neg_hi:[0,0,1]
	v_pk_fma_f32 v[34:35], v[36:37], v[44:45], v[40:41]
	v_pk_fma_f32 v[36:37], v[56:57], v[46:47], v[62:63] neg_lo:[0,0,1] neg_hi:[0,0,1]
	v_pk_fma_f32 v[38:39], v[38:39], v[46:47], v[42:43]
	v_pk_fma_f32 v[40:41], v[52:53], v[66:67], v[70:71] neg_lo:[0,0,1] neg_hi:[0,0,1]
	v_pk_fma_f32 v[42:43], v[58:59], v[66:67], v[72:73]
	v_pk_fma_f32 v[44:45], v[48:49], v[68:69], v[74:75] neg_lo:[0,0,1] neg_hi:[0,0,1]
	v_pk_fma_f32 v[46:47], v[54:55], v[68:69], v[76:77]
	v_lshlrev_b64 v[56:57], 7, v[64:65]
	v_cvt_pk_bf16_f32 v48, v32, v33
	v_cvt_pk_bf16_f32 v49, v36, v37
	v_cvt_pk_bf16_f32 v50, v40, v41
	v_cvt_pk_bf16_f32 v51, v44, v45
	v_cvt_pk_bf16_f32 v52, v34, v35
	v_cvt_pk_bf16_f32 v53, v38, v39
	v_cvt_pk_bf16_f32 v54, v42, v43
	v_cvt_pk_bf16_f32 v55, v46, v47
	v_lshl_add_u64 v[56:57], v[178:179], 0, v[56:57]
	v_lshl_add_u64 v[226:227], v[56:57], 0, v[222:223]
	v_lshl_add_u64 v[228:229], v[226:227], 0, s[90:91]
	global_store_dwordx4 v[226:227], v[48:51], off
	global_store_dwordx4 v[228:229], v[52:55], off
	s_cbranch_vccnz .LBB0_436
	v_pk_add_f32 v[202:203], v[202:203], v[32:33]
	v_pk_add_f32 v[198:199], v[198:199], v[34:35]
	v_pk_add_f32 v[138:139], v[138:139], v[36:37]
	v_pk_add_f32 v[136:137], v[136:137], v[38:39]
	v_pk_add_f32 v[134:135], v[134:135], v[40:41]
	v_pk_add_f32 v[132:133], v[132:133], v[42:43]
	v_pk_add_f32 v[130:131], v[130:131], v[44:45]
	v_pk_add_f32 v[128:129], v[128:129], v[46:47]
; DI unsigned cvt_pk(float lo, float hi) { const f32x2 v = {lo, hi}; return __builtin_bit_cast(unsigned, __builtin_convertvector(v, bf16v2)); }
;     __device__ __forceinline__ void operator()(const f32x4 (&acc)[2][2][4][2], const Unit& u, int wr, int wc, int fr, int fq) const {
;     ...
;                 for (int m = 0; m < 4; ++m) {
;                     const int s = sbase + ai * 128 + m * 16; const float r = ROW_RS(ai, m);
;                     float t0[8], t1[8]; float ss = 0.f;
; #pragma unroll
;                     for (int n = 0; n < 2; ++n)
; #pragma unroll
;                         for (int j = 0; j < 4; ++j) { t0[4 * n + j] = acc[ai][0][m][n][j]; t1[4 * n + j] = acc[ai][1][m][n][j]; }
; #pragma unroll
;                     for (int i = 0; i < 8; ++i) ss += t0[i] * t0[i] + t1[i] * t1[i];
;                     ss += __shfl_xor(ss, 16); ss += __shfl_xor(ss, 32);
;                     const float hr = r * rsqrtf(ss * (r * r) * (1.0f / 64.0f) + NORM_EPS);
;                     const f32x4* cp = (const f32x4*)(cs + (size_t)s * 32 + 8 * fq);
;                     float o0[8], o1[8];
; #pragma unroll
;                     for (int q = 0; q < 4; ++q) { const f32x4 c4 = cp[q];
;                         { const int i = 2 * q; const float a = t0[i] * hr * g0[i], bb = t1[i] * hr * g1[i]; o0[i] = a * c4[0] - bb * c4[1]; o1[i] = bb * c4[0] + a * c4[1]; }
;                         { const int i = 2 * q + 1; const float a = t0[i] * hr * g0[i], bb = t1[i] * hr * g1[i]; o0[i] = a * c4[2] - bb * c4[3]; o1[i] = bb * c4[2] + a * c4[3]; } }
;                     u32x4 w0, w1;
;                     w0.x = cvt_pk(o0[0], o0[1]); w0.y = cvt_pk(o0[2], o0[3]); w0.z = cvt_pk(o0[4], o0[5]); w0.w = cvt_pk(o0[6], o0[7]);
;                     w1.x = cvt_pk(o1[0], o1[1]); w1.y = cvt_pk(o1[2], o1[3]); w1.z = cvt_pk(o1[4], o1[5]); w1.w = cvt_pk(o1[6], o1[7]);
;                     bf16_t* rp = dst + ((bh * SEQ + s) * 64 + 8 * fq);
;                     *(u32x4*)rp = w0; *(u32x4*)(rp + 32) = w1;
;                     if (do_km) {
; #pragma unroll
;                         for (int i = 0; i < 8; ++i) { cs0[i] += o0[i]; cs1[i] += o1[i]; }
;                     }
.LBB0_436:
	v_add_u32_e32 v48, 0xa0, v168
	v_ashrrev_i32_e32 v49, 31, v48
	v_lshlrev_b64 v[32:33], 8, v[48:49]
	v_lshl_add_u64 v[32:33], v[152:153], 0, v[32:33]
	global_load_dwordx4 v[44:47], v[32:33], off
	global_load_dwordx4 v[40:43], v[32:33], off offset:16
	global_load_dwordx4 v[36:39], v[32:33], off offset:32
	s_nop 0
	global_load_dwordx4 v[32:35], v[32:33], off offset:48
	v_pk_mul_f32 v[52:53], v[24:25], v[24:25]
	v_pk_mul_f32 v[50:51], v[26:27], v[26:27]
	v_pk_fma_f32 v[52:53], v[28:29], v[28:29], v[52:53]
	v_pk_fma_f32 v[50:51], v[30:31], v[30:31], v[50:51]
	v_add_f32_e32 v52, v52, v53
	v_pk_mul_f32 v[56:57], v[16:17], v[16:17]
	v_add_f32_e32 v50, v50, v52
	v_pk_fma_f32 v[56:57], v[20:21], v[20:21], v[56:57]
	v_add_f32_e32 v50, v51, v50
	v_pk_mul_f32 v[54:55], v[18:19], v[18:19]
	v_add_f32_e32 v50, v56, v50
	v_pk_fma_f32 v[54:55], v[22:23], v[22:23], v[54:55]
	v_add_f32_e32 v50, v57, v50
	v_add_f32_e32 v50, v54, v50
	v_add_f32_e32 v50, v55, v50
	ds_bpermute_b32 v51, v206, v50
	v_mul_f32_e32 v52, v170, v170
	s_waitcnt lgkmcnt(0)
	v_add_f32_e32 v50, v50, v51
	ds_bpermute_b32 v51, v207, v50
	s_waitcnt lgkmcnt(0)
	v_add_f32_e32 v50, v50, v51
	v_mul_f32_e32 v50, v52, v50
	v_fmamk_f32 v50, v50, 0x3c800000, v177
	v_mul_f32_e32 v51, 0x4b800000, v50
	v_cmp_gt_f32_e32 vcc, s23, v50
	s_nop 1
	v_cndmask_b32_e32 v50, v50, v51, vcc
	v_rsq_f32_e32 v50, v50
	s_nop 0
	v_mul_f32_e32 v51, 0x45800000, v50
	v_cndmask_b32_e32 v50, v50, v51, vcc
	v_mul_f32_e32 v50, v170, v50
	v_pk_mul_f32 v[24:25], v[24:25], v[50:51] op_sel_hi:[1,0]
	v_pk_mul_f32 v[26:27], v[26:27], v[50:51] op_sel_hi:[1,0]
	v_pk_mul_f32 v[20:21], v[20:21], v[50:51] op_sel_hi:[1,0]
	v_pk_mul_f32 v[16:17], v[16:17], v[50:51] op_sel_hi:[1,0]
	v_pk_mul_f32 v[22:23], v[22:23], v[50:51] op_sel_hi:[1,0]
	v_pk_mul_f32 v[18:19], v[18:19], v[50:51] op_sel_hi:[1,0]
	v_pk_mul_f32 v[28:29], v[28:29], v[50:51] op_sel_hi:[1,0]
	v_pk_mul_f32 v[30:31], v[30:31], v[50:51] op_sel_hi:[1,0]
	v_pk_mul_f32 v[24:25], v[186:187], v[24:25]
	v_pk_mul_f32 v[26:27], v[190:191], v[26:27]
	v_pk_mul_f32 v[50:51], v[192:193], v[20:21]
	v_pk_mul_f32 v[16:17], v[194:195], v[16:17]
	v_pk_mul_f32 v[52:53], v[196:197], v[22:23]
	v_pk_mul_f32 v[18:19], v[182:183], v[18:19]
	v_pk_mul_f32 v[28:29], v[184:185], v[28:29]
	v_pk_mul_f32 v[30:31], v[188:189], v[30:31]
	s_and_b64 vcc, exec, s[6:7]
	s_waitcnt vmcnt(3)
	v_mov_b32_e32 v20, v44
	v_mov_b32_e32 v21, v46
	v_mov_b32_e32 v46, v45
	s_waitcnt vmcnt(2)
	v_mov_b32_e32 v22, v40
	v_mov_b32_e32 v23, v42
	v_mov_b32_e32 v42, v41
	s_waitcnt vmcnt(1)
	v_mov_b32_e32 v40, v36
	v_mov_b32_e32 v41, v38
	v_mov_b32_e32 v38, v37
	s_waitcnt vmcnt(0)
	v_mov_b32_e32 v36, v32
	v_mov_b32_e32 v37, v34
	v_mov_b32_e32 v34, v33
	v_pk_mul_f32 v[32:33], v[46:47], v[24:25]
	v_pk_mul_f32 v[24:25], v[20:21], v[24:25]
	v_pk_mul_f32 v[44:45], v[42:43], v[26:27]
	v_pk_mul_f32 v[26:27], v[22:23], v[26:27]
	v_pk_mul_f32 v[54:55], v[38:39], v[16:17]
	v_pk_mul_f32 v[56:57], v[40:41], v[16:17]
	v_pk_mul_f32 v[58:59], v[34:35], v[18:19]
	v_pk_mul_f32 v[60:61], v[36:37], v[18:19]
	v_pk_fma_f32 v[16:17], v[20:21], v[28:29], v[32:33] neg_lo:[0,0,1] neg_hi:[0,0,1]
	v_pk_fma_f32 v[18:19], v[46:47], v[28:29], v[24:25]
	v_pk_fma_f32 v[20:21], v[22:23], v[30:31], v[44:45] neg_lo:[0,0,1] neg_hi:[0,0,1]
	v_pk_fma_f32 v[22:23], v[42:43], v[30:31], v[26:27]
	v_pk_fma_f32 v[24:25], v[40:41], v[50:51], v[54:55] neg_lo:[0,0,1] neg_hi:[0,0,1]
	v_pk_fma_f32 v[26:27], v[38:39], v[50:51], v[56:57]
	v_pk_fma_f32 v[28:29], v[36:37], v[52:53], v[58:59] neg_lo:[0,0,1] neg_hi:[0,0,1]
	v_pk_fma_f32 v[30:31], v[34:35], v[52:53], v[60:61]
	v_lshlrev_b64 v[40:41], 7, v[48:49]
	v_cvt_pk_bf16_f32 v32, v16, v17
	v_cvt_pk_bf16_f32 v33, v20, v21
	v_cvt_pk_bf16_f32 v34, v24, v25
	v_cvt_pk_bf16_f32 v35, v28, v29
	v_cvt_pk_bf16_f32 v36, v18, v19
	v_cvt_pk_bf16_f32 v37, v22, v23
	v_cvt_pk_bf16_f32 v38, v26, v27
	v_cvt_pk_bf16_f32 v39, v30, v31
	v_lshl_add_u64 v[40:41], v[178:179], 0, v[40:41]
	v_lshl_add_u64 v[226:227], v[40:41], 0, v[220:221]
	v_lshl_add_u64 v[228:229], v[226:227], 0, s[90:91]
	global_store_dwordx4 v[226:227], v[32:35], off
	global_store_dwordx4 v[228:229], v[36:39], off
	s_cbranch_vccnz .LBB0_438
	v_pk_add_f32 v[202:203], v[202:203], v[16:17]
	v_pk_add_f32 v[198:199], v[198:199], v[18:19]
	v_pk_add_f32 v[138:139], v[138:139], v[20:21]
	v_pk_add_f32 v[136:137], v[136:137], v[22:23]
	v_pk_add_f32 v[134:135], v[134:135], v[24:25]
	v_pk_add_f32 v[132:133], v[132:133], v[26:27]
	v_pk_add_f32 v[130:131], v[130:131], v[28:29]
	v_pk_add_f32 v[128:129], v[128:129], v[30:31]
; DI unsigned cvt_pk(float lo, float hi) { const f32x2 v = {lo, hi}; return __builtin_bit_cast(unsigned, __builtin_convertvector(v, bf16v2)); }
;     __device__ __forceinline__ void operator()(const f32x4 (&acc)[2][2][4][2], const Unit& u, int wr, int wc, int fr, int fq) const {
;     ...
;                 for (int m = 0; m < 4; ++m) {
;                     const int s = sbase + ai * 128 + m * 16; const float r = ROW_RS(ai, m);
;                     float t0[8], t1[8]; float ss = 0.f;
; #pragma unroll
;                     for (int n = 0; n < 2; ++n)
; #pragma unroll
;                         for (int j = 0; j < 4; ++j) { t0[4 * n + j] = acc[ai][0][m][n][j]; t1[4 * n + j] = acc[ai][1][m][n][j]; }
; #pragma unroll
;                     for (int i = 0; i < 8; ++i) ss += t0[i] * t0[i] + t1[i] * t1[i];
;                     ss += __shfl_xor(ss, 16); ss += __shfl_xor(ss, 32);
;                     const float hr = r * rsqrtf(ss * (r * r) * (1.0f / 64.0f) + NORM_EPS);
;                     const f32x4* cp = (const f32x4*)(cs + (size_t)s * 32 + 8 * fq);
;                     float o0[8], o1[8];
; #pragma unroll
;                     for (int q = 0; q < 4; ++q) { const f32x4 c4 = cp[q];
;                         { const int i = 2 * q; const float a = t0[i] * hr * g0[i], bb = t1[i] * hr * g1[i]; o0[i] = a * c4[0] - bb * c4[1]; o1[i] = bb * c4[0] + a * c4[1]; }
;                         { const int i = 2 * q + 1; const float a = t0[i] * hr * g0[i], bb = t1[i] * hr * g1[i]; o0[i] = a * c4[2] - bb * c4[3]; o1[i] = bb * c4[2] + a * c4[3]; } }
;                     u32x4 w0, w1;
;                     w0.x = cvt_pk(o0[0], o0[1]); w0.y = cvt_pk(o0[2], o0[3]); w0.z = cvt_pk(o0[4], o0[5]); w0.w = cvt_pk(o0[6], o0[7]);
;                     w1.x = cvt_pk(o1[0], o1[1]); w1.y = cvt_pk(o1[2], o1[3]); w1.z = cvt_pk(o1[4], o1[5]); w1.w = cvt_pk(o1[6], o1[7]);
;                     bf16_t* rp = dst + ((bh * SEQ + s) * 64 + 8 * fq);
;                     *(u32x4*)rp = w0; *(u32x4*)(rp + 32) = w1;
;                     if (do_km) {
; #pragma unroll
;                         for (int i = 0; i < 8; ++i) { cs0[i] += o0[i]; cs1[i] += o1[i]; }
;                     }
.LBB0_438:
	v_add_u32_e32 v32, 0xb0, v168
	v_ashrrev_i32_e32 v33, 31, v32
	v_lshlrev_b64 v[16:17], 8, v[32:33]
	v_lshl_add_u64 v[16:17], v[152:153], 0, v[16:17]
	global_load_dwordx4 v[28:31], v[16:17], off
	global_load_dwordx4 v[24:27], v[16:17], off offset:16
	global_load_dwordx4 v[20:23], v[16:17], off offset:32
	s_nop 0
	global_load_dwordx4 v[16:19], v[16:17], off offset:48
	v_pk_mul_f32 v[36:37], v[8:9], v[8:9]
	v_pk_mul_f32 v[34:35], v[10:11], v[10:11]
	v_pk_fma_f32 v[36:37], v[12:13], v[12:13], v[36:37]
	v_pk_fma_f32 v[34:35], v[14:15], v[14:15], v[34:35]
	v_add_f32_e32 v36, v36, v37
	v_pk_mul_f32 v[40:41], v[0:1], v[0:1]
	v_add_f32_e32 v34, v34, v36
	v_pk_fma_f32 v[40:41], v[4:5], v[4:5], v[40:41]
	v_add_f32_e32 v34, v35, v34
	v_pk_mul_f32 v[38:39], v[2:3], v[2:3]
	v_add_f32_e32 v34, v40, v34
	v_pk_fma_f32 v[38:39], v[6:7], v[6:7], v[38:39]
	v_add_f32_e32 v34, v41, v34
	v_add_f32_e32 v34, v38, v34
	v_add_f32_e32 v34, v39, v34
	ds_bpermute_b32 v35, v206, v34
	v_mul_f32_e32 v36, v166, v166
	s_waitcnt lgkmcnt(0)
	v_add_f32_e32 v34, v34, v35
	ds_bpermute_b32 v35, v207, v34
	s_waitcnt lgkmcnt(0)
	v_add_f32_e32 v34, v34, v35
	v_mul_f32_e32 v34, v36, v34
	v_fmamk_f32 v34, v34, 0x3c800000, v177
	v_mul_f32_e32 v35, 0x4b800000, v34
	v_cmp_gt_f32_e32 vcc, s23, v34
	s_nop 1
	v_cndmask_b32_e32 v34, v34, v35, vcc
	v_rsq_f32_e32 v34, v34
	s_nop 0
	v_mul_f32_e32 v35, 0x45800000, v34
	v_cndmask_b32_e32 v34, v34, v35, vcc
	v_mul_f32_e32 v34, v166, v34
	v_pk_mul_f32 v[8:9], v[8:9], v[34:35] op_sel_hi:[1,0]
	v_pk_mul_f32 v[10:11], v[10:11], v[34:35] op_sel_hi:[1,0]
	v_pk_mul_f32 v[4:5], v[4:5], v[34:35] op_sel_hi:[1,0]
	v_pk_mul_f32 v[0:1], v[0:1], v[34:35] op_sel_hi:[1,0]
	v_pk_mul_f32 v[2:3], v[2:3], v[34:35] op_sel_hi:[1,0]
	v_pk_mul_f32 v[12:13], v[12:13], v[34:35] op_sel_hi:[1,0]
	v_pk_mul_f32 v[14:15], v[14:15], v[34:35] op_sel_hi:[1,0]
	v_pk_mul_f32 v[6:7], v[6:7], v[34:35] op_sel_hi:[1,0]
	v_pk_mul_f32 v[8:9], v[186:187], v[8:9]
	v_pk_mul_f32 v[10:11], v[190:191], v[10:11]
	v_pk_mul_f32 v[34:35], v[192:193], v[4:5]
	v_pk_mul_f32 v[0:1], v[194:195], v[0:1]
	v_pk_mul_f32 v[2:3], v[182:183], v[2:3]
	v_pk_mul_f32 v[12:13], v[184:185], v[12:13]
	v_pk_mul_f32 v[14:15], v[188:189], v[14:15]
	v_pk_mul_f32 v[36:37], v[196:197], v[6:7]
	s_and_b64 vcc, exec, s[6:7]
	s_waitcnt vmcnt(3)
	v_mov_b32_e32 v4, v28
	v_mov_b32_e32 v5, v30
	v_mov_b32_e32 v30, v29
	s_waitcnt vmcnt(2)
	v_mov_b32_e32 v28, v24
	v_mov_b32_e32 v29, v26
	v_mov_b32_e32 v26, v25
	s_waitcnt vmcnt(1)
	v_mov_b32_e32 v24, v20
	v_mov_b32_e32 v25, v22
	v_mov_b32_e32 v22, v21
	s_waitcnt vmcnt(0)
	v_mov_b32_e32 v20, v16
	v_mov_b32_e32 v21, v18
	v_mov_b32_e32 v18, v17
	v_pk_mul_f32 v[6:7], v[30:31], v[8:9]
	v_pk_mul_f32 v[8:9], v[4:5], v[8:9]
	v_pk_mul_f32 v[16:17], v[26:27], v[10:11]
	v_pk_mul_f32 v[10:11], v[28:29], v[10:11]
	v_pk_mul_f32 v[38:39], v[22:23], v[0:1]
	v_pk_mul_f32 v[0:1], v[24:25], v[0:1]
	v_pk_mul_f32 v[40:41], v[18:19], v[2:3]
	v_pk_mul_f32 v[42:43], v[20:21], v[2:3]
	v_pk_fma_f32 v[6:7], v[4:5], v[12:13], v[6:7] neg_lo:[0,0,1] neg_hi:[0,0,1]
	v_pk_fma_f32 v[4:5], v[30:31], v[12:13], v[8:9]
	v_pk_fma_f32 v[16:17], v[28:29], v[14:15], v[16:17] neg_lo:[0,0,1] neg_hi:[0,0,1]
	v_pk_fma_f32 v[12:13], v[26:27], v[14:15], v[10:11]
	v_pk_fma_f32 v[14:15], v[24:25], v[34:35], v[38:39] neg_lo:[0,0,1] neg_hi:[0,0,1]
	v_pk_fma_f32 v[10:11], v[22:23], v[34:35], v[0:1]
	v_pk_fma_f32 v[2:3], v[20:21], v[36:37], v[40:41] neg_lo:[0,0,1] neg_hi:[0,0,1]
	v_pk_fma_f32 v[0:1], v[18:19], v[36:37], v[42:43]
	v_lshlrev_b64 v[8:9], 7, v[32:33]
	v_cvt_pk_bf16_f32 v18, v6, v7
	v_cvt_pk_bf16_f32 v19, v16, v17
	v_cvt_pk_bf16_f32 v20, v14, v15
	v_cvt_pk_bf16_f32 v21, v2, v3
	v_cvt_pk_bf16_f32 v22, v4, v5
	v_cvt_pk_bf16_f32 v23, v12, v13
	v_cvt_pk_bf16_f32 v24, v10, v11
	v_cvt_pk_bf16_f32 v25, v0, v1
	v_lshl_add_u64 v[8:9], v[178:179], 0, v[8:9]
	v_lshl_add_u64 v[226:227], v[8:9], 0, v[222:223]
	v_lshl_add_u64 v[228:229], v[226:227], 0, s[90:91]
	global_store_dwordx4 v[226:227], v[18:21], off
	global_store_dwordx4 v[228:229], v[22:25], off
	s_cbranch_vccnz .LBB0_442
;     __device__ __forceinline__ void operator()(const f32x4 (&acc)[2][2][4][2], const Unit& u, int wr, int wc, int fr, int fq) const {
;     ...
;             if (do_km) {
; #pragma unroll
;                 for (int i = 0; i < 8; ++i) {
; #pragma unroll
;                     for (int o = 1; o <= 8; o <<= 1) { cs0[i] += __shfl_xor(cs0[i], o); cs1[i] += __shfl_xor(cs1[i], o); }
;                 }
;                 if (fr == 0) {
;                     float* kp = kmp + (((size_t)wr * 64 + bh) * 16 + (u.pm & 15)) * 64 + 8 * fq;
;                     *(f32x4*)kp = (f32x4){cs0[0], cs0[1], cs0[2], cs0[3]}; *(f32x4*)(kp + 4) = (f32x4){cs0[4], cs0[5], cs0[6], cs0[7]};
;                     *(f32x4*)(kp + 32) = (f32x4){cs1[0], cs1[1], cs1[2], cs1[3]}; *(f32x4*)(kp + 36) = (f32x4){cs1[4], cs1[5], cs1[6], cs1[7]};
;                 }
	v_xor_b32_e32 v8, 1, v181
	v_cmp_lt_i32_e32 vcc, v8, v201
	v_pk_add_f32 v[24:25], v[134:135], v[14:15]
	v_pk_add_f32 v[4:5], v[198:199], v[4:5]
	v_cndmask_b32_e32 v8, v181, v8, vcc
	v_lshlrev_b32_e32 v33, 2, v8
	v_xor_b32_e32 v8, 2, v181
	v_cmp_lt_i32_e32 vcc, v8, v201
	ds_bpermute_b32 v26, v33, v24
	ds_bpermute_b32 v27, v33, v25
	v_cndmask_b32_e32 v8, v181, v8, vcc
	v_lshlrev_b32_e32 v34, 2, v8
	v_xor_b32_e32 v8, 4, v181
	v_cmp_lt_i32_e32 vcc, v8, v201
	ds_bpermute_b32 v18, v33, v4
	ds_bpermute_b32 v19, v33, v5
	v_cndmask_b32_e32 v20, v181, v8, vcc
	v_lshlrev_b32_e32 v35, 2, v20
	v_xor_b32_e32 v20, 8, v181
	v_cmp_lt_i32_e32 vcc, v20, v201
	s_waitcnt lgkmcnt(0)
	v_pk_add_f32 v[4:5], v[4:5], v[18:19]
	ds_bpermute_b32 v18, v34, v4
	v_cndmask_b32_e32 v20, v181, v20, vcc
	v_lshlrev_b32_e32 v36, 2, v20
	v_pk_add_f32 v[20:21], v[136:137], v[12:13]
	ds_bpermute_b32 v22, v33, v20
	ds_bpermute_b32 v23, v33, v21
	ds_bpermute_b32 v19, v34, v5
	v_pk_add_f32 v[6:7], v[202:203], v[6:7]
	v_pk_add_f32 v[16:17], v[138:139], v[16:17]
	v_pk_add_f32 v[2:3], v[130:131], v[2:3]
	s_waitcnt lgkmcnt(1)
	v_pk_add_f32 v[20:21], v[20:21], v[22:23]
	ds_bpermute_b32 v22, v34, v20
	ds_bpermute_b32 v23, v34, v21
	s_waitcnt lgkmcnt(2)
	v_pk_add_f32 v[4:5], v[4:5], v[18:19]
	ds_bpermute_b32 v18, v35, v4
	ds_bpermute_b32 v19, v35, v5
	v_pk_add_f32 v[30:31], v[128:129], v[0:1]
	s_waitcnt lgkmcnt(2)
	v_pk_add_f32 v[20:21], v[20:21], v[22:23]
	ds_bpermute_b32 v22, v35, v20
	ds_bpermute_b32 v23, v35, v21
	ds_bpermute_b32 v8, v33, v6
	ds_bpermute_b32 v9, v33, v7
	s_waitcnt lgkmcnt(4)
	v_pk_add_f32 v[4:5], v[4:5], v[18:19]
	ds_bpermute_b32 v18, v33, v16
	s_waitcnt lgkmcnt(3)
	v_pk_add_f32 v[14:15], v[20:21], v[22:23]
	v_pk_add_f32 v[20:21], v[24:25], v[26:27]
	v_pk_add_f32 v[24:25], v[132:133], v[10:11]
	ds_bpermute_b32 v26, v33, v24
	ds_bpermute_b32 v27, v33, v25
	ds_bpermute_b32 v19, v33, v17
	ds_bpermute_b32 v28, v33, v2
	ds_bpermute_b32 v29, v33, v3
	ds_bpermute_b32 v32, v33, v30
	s_waitcnt lgkmcnt(4)
	v_pk_add_f32 v[24:25], v[24:25], v[26:27]
	ds_bpermute_b32 v26, v34, v24
	ds_bpermute_b32 v27, v34, v25
	ds_bpermute_b32 v33, v33, v31
	v_pk_add_f32 v[6:7], v[6:7], v[8:9]
	s_waitcnt lgkmcnt(6)
	v_pk_add_f32 v[16:17], v[16:17], v[18:19]
	ds_bpermute_b32 v8, v34, v6
	s_waitcnt lgkmcnt(2)
	v_pk_add_f32 v[24:25], v[24:25], v[26:27]
	ds_bpermute_b32 v26, v35, v24
	ds_bpermute_b32 v27, v35, v25
	ds_bpermute_b32 v9, v34, v7
	ds_bpermute_b32 v18, v34, v16
	ds_bpermute_b32 v19, v34, v17
	ds_bpermute_b32 v22, v34, v20
	s_waitcnt lgkmcnt(4)
	v_pk_add_f32 v[0:1], v[24:25], v[26:27]
	v_pk_add_f32 v[24:25], v[2:3], v[28:29]
	v_pk_add_f32 v[28:29], v[30:31], v[32:33]
	ds_bpermute_b32 v23, v34, v21
	ds_bpermute_b32 v26, v34, v24
	ds_bpermute_b32 v27, v34, v25
	ds_bpermute_b32 v30, v34, v28
	ds_bpermute_b32 v31, v34, v29
	s_waitcnt lgkmcnt(8)
	v_pk_add_f32 v[6:7], v[6:7], v[8:9]
	s_waitcnt lgkmcnt(6)
	v_pk_add_f32 v[16:17], v[16:17], v[18:19]
	s_waitcnt lgkmcnt(4)
	v_pk_add_f32 v[20:21], v[20:21], v[22:23]
	s_waitcnt lgkmcnt(2)
	v_pk_add_f32 v[24:25], v[24:25], v[26:27]
	s_waitcnt lgkmcnt(0)
	v_pk_add_f32 v[32:33], v[28:29], v[30:31]
	ds_bpermute_b32 v8, v35, v6
	ds_bpermute_b32 v9, v35, v7
	ds_bpermute_b32 v18, v35, v16
	ds_bpermute_b32 v19, v35, v17
	ds_bpermute_b32 v22, v35, v20
	ds_bpermute_b32 v23, v35, v21
	ds_bpermute_b32 v26, v35, v24
	ds_bpermute_b32 v27, v35, v25
	ds_bpermute_b32 v34, v35, v32
	ds_bpermute_b32 v35, v35, v33
	s_waitcnt lgkmcnt(8)
	v_pk_add_f32 v[6:7], v[6:7], v[8:9]
	s_waitcnt lgkmcnt(6)
	v_pk_add_f32 v[16:17], v[16:17], v[18:19]
	s_waitcnt lgkmcnt(4)
	v_pk_add_f32 v[20:21], v[20:21], v[22:23]
	s_waitcnt lgkmcnt(2)
	v_pk_add_f32 v[28:29], v[24:25], v[26:27]
	s_waitcnt lgkmcnt(0)
	v_pk_add_f32 v[24:25], v[32:33], v[34:35]
	ds_bpermute_b32 v8, v36, v6
	ds_bpermute_b32 v12, v36, v4
	ds_bpermute_b32 v9, v36, v7
	ds_bpermute_b32 v13, v36, v5
	ds_bpermute_b32 v18, v36, v16
	ds_bpermute_b32 v10, v36, v14
	ds_bpermute_b32 v19, v36, v17
	ds_bpermute_b32 v11, v36, v15
	ds_bpermute_b32 v22, v36, v20
	ds_bpermute_b32 v2, v36, v0
	ds_bpermute_b32 v23, v36, v21
	ds_bpermute_b32 v3, v36, v1
	ds_bpermute_b32 v30, v36, v28
	ds_bpermute_b32 v26, v36, v24
	ds_bpermute_b32 v31, v36, v29
	ds_bpermute_b32 v27, v36, v25
	s_and_saveexec_b64 s[6:7], s[0:1]
	s_cbranch_execz .LBB0_441
	s_lshl_b64 s[44:45], s[82:83], 4
	s_add_u32 s2, s44, s72
	s_addc_u32 s45, s45, s73
	s_and_b32 s10, s10, 15
	s_or_b32 s44, s2, s10
	s_lshl_b64 s[44:45], s[44:45], 8
	v_lshl_add_u64 v[32:33], v[154:155], 0, s[44:45]
	s_waitcnt lgkmcnt(9)
	v_pk_add_f32 v[18:19], v[16:17], v[18:19]
	v_pk_add_f32 v[16:17], v[6:7], v[8:9]
	s_waitcnt lgkmcnt(1)
	v_pk_add_f32 v[8:9], v[28:29], v[30:31]
	v_pk_add_f32 v[6:7], v[20:21], v[22:23]
	global_store_dwordx4 v[32:33], v[6:9], off offset:16
	v_pk_add_f32 v[4:5], v[4:5], v[12:13]
	v_pk_add_f32 v[2:3], v[0:1], v[2:3]
	v_pk_add_f32 v[6:7], v[14:15], v[10:11]
	global_store_dwordx4 v[32:33], v[4:7], off offset:128
	global_store_dwordx4 v[32:33], v[16:19], off
	s_waitcnt lgkmcnt(0)
	v_pk_add_f32 v[4:5], v[24:25], v[26:27]
	global_store_dwordx4 v[32:33], v[2:5], off offset:144

; DI void tile_gload(TileRegs& t, const bf16_t* K, const bf16_t* V, int kbase, int kstride, int lane) {
;     const int row0 = lane >> 3, ch = lane & 7;
; #pragma unroll
;     for (int i = 0; i < 4; ++i) {
;         const unsigned off = (unsigned)((kbase + kstride * (row0 + 8 * i)) * 128 + ch * 16);
;         t.k[i] = *(const u32x4*)((const unsigned char*)K + off); t.v[i] = *(const u32x4*)((const unsigned char*)V + off);
;     }
; DI void attn_b_item(unsigned char* ws, LAS unsigned char* buf, LAS unsigned char* qbuf, LAS unsigned* tbl, LAS float* km  , int bh, int qblk, int w4, int lane) {
;     ...
;         int nc = __builtin_ctz(uni), Tc = 0;
;         tile_gload(tr, K, V, nc * 256, 1, lane);
.LBB0_562:
	s_lshl_b32 s16, s81, 1
	s_add_u32 s78, s38, s16
	s_addc_u32 s79, s39, 0
	s_add_u32 s80, s64, s16
	s_addc_u32 s81, s65, 0
	s_andn2_b32 s16, s18, s56
	s_lshl_b32 s17, 1, s57
	s_or_b32 s85, s16, s17
	s_ff1_i32_b32 s20, s85
	s_lshl_b32 s16, s20, 8
	v_mbcnt_hi_u32_b32 v206, -1, v224
	v_lshlrev_b32_e32 v206, 4, v206
	s_lshl_b32 s16, s16, 7
	v_add_u32_e32 v207, s16, v206
	global_load_dwordx4 v[152:155], v207, s[80:81]
	global_load_dwordx4 v[160:163], v207, s[80:81] offset:1024
	global_load_dwordx4 v[168:171], v207, s[80:81] offset:2048
	global_load_dwordx4 v[176:179], v207, s[80:81] offset:3072
	global_load_dwordx4 v[148:151], v207, s[78:79]
	global_load_dwordx4 v[156:159], v207, s[78:79] offset:1024
	global_load_dwordx4 v[164:167], v207, s[78:79] offset:2048
	global_load_dwordx4 v[172:175], v207, s[78:79] offset:3072
	s_lshl_b32 s86, s82, 1
	v_xor_b32_e32 v64, 0x80000000, v247
	v_mov_b32_e32 v183, 0
	s_add_i32 s87, s86, 2
	v_mov_b32_e32 v65, v64
	v_mov_b32_e32 v66, v64
	v_mov_b32_e32 v67, v64
	v_mov_b32_e32 v68, v64
	v_mov_b32_e32 v69, v64
	v_mov_b32_e32 v70, v64
	v_mov_b32_e32 v71, v64
	v_mov_b32_e32 v72, v64
	v_mov_b32_e32 v73, v64
	v_mov_b32_e32 v74, v64
	v_mov_b32_e32 v75, v64
	v_mov_b32_e32 v76, v64
	v_mov_b32_e32 v77, v64
	v_mov_b32_e32 v78, v64
	v_mov_b32_e32 v79, v64
	s_mov_b32 s21, 0
	v_mov_b32_e32 v189, 0
	v_mov_b32_e32 v48, 0
	v_mov_b32_e32 v49, v183
	v_mov_b32_e32 v50, v183
	v_mov_b32_e32 v51, v183
	v_mov_b32_e32 v52, v183
	v_mov_b32_e32 v53, v183
	v_mov_b32_e32 v54, v183
	v_mov_b32_e32 v55, v183
	v_mov_b32_e32 v56, v183
	v_mov_b32_e32 v57, v183
	v_mov_b32_e32 v58, v183
	v_mov_b32_e32 v59, v183
	v_mov_b32_e32 v60, v183
	v_mov_b32_e32 v61, v183
	v_mov_b32_e32 v62, v183
	v_mov_b32_e32 v63, v183
	v_mov_b32_e32 v32, 0
	v_mov_b32_e32 v33, v183
	v_mov_b32_e32 v34, v183
	v_mov_b32_e32 v35, v183
	v_mov_b32_e32 v36, v183
	v_mov_b32_e32 v37, v183
	v_mov_b32_e32 v38, v183
	v_mov_b32_e32 v39, v183
	v_mov_b32_e32 v40, v183
	v_mov_b32_e32 v41, v183
	v_mov_b32_e32 v42, v183
	v_mov_b32_e32 v43, v183
	v_mov_b32_e32 v44, v183
	v_mov_b32_e32 v45, v183
	v_mov_b32_e32 v46, v183
	v_mov_b32_e32 v47, v183
	v_mov_b32_e32 v0, 0
	v_mov_b32_e32 v1, v183
	v_mov_b32_e32 v2, v183
	v_mov_b32_e32 v3, v183
	v_mov_b32_e32 v4, v183
	v_mov_b32_e32 v5, v183
	v_mov_b32_e32 v6, v183
	v_mov_b32_e32 v7, v183
	v_mov_b32_e32 v8, v183
	v_mov_b32_e32 v9, v183
	v_mov_b32_e32 v10, v183
	v_mov_b32_e32 v11, v183
	v_mov_b32_e32 v12, v183
	v_mov_b32_e32 v13, v183
	v_mov_b32_e32 v14, v183
	v_mov_b32_e32 v15, v183
	v_mov_b32_e32 v16, 0
	v_mov_b32_e32 v17, v183
	v_mov_b32_e32 v18, v183
	v_mov_b32_e32 v19, v183
	v_mov_b32_e32 v20, v183
	v_mov_b32_e32 v21, v183
	v_mov_b32_e32 v22, v183
	v_mov_b32_e32 v23, v183
	v_mov_b32_e32 v24, v183
	v_mov_b32_e32 v25, v183
	v_mov_b32_e32 v26, v183
	v_mov_b32_e32 v27, v183
	v_mov_b32_e32 v28, v183
	v_mov_b32_e32 v29, v183
	v_mov_b32_e32 v30, v183
	v_mov_b32_e32 v31, v183
; #define MFMA32(a, b, c) __builtin_amdgcn_mfma_f32_32x32x16_bf16((a), (b), (c), 0, 0, 0)
; #define B_ADV(n_, T_, ok_) do { const int cnt_ = ((n_) == qblk) ? own_tiles : 8; if (++(T_) >= cnt_) { const unsigned rest_ = uni & ~((2u << (n_)) - 1u); if (rest_) { (n_) = __builtin_ctz(rest_); (T_) = 0; } else (ok_) = false; } } while (0)
; DI void core2(QT& a, QT& b, LAS unsigned char* buf, int dist0a, int dist0b, int kstride, int hi, bool elem, bool oka, bool okb, float m0, int lane) {
;     ...
;     {
;         const float c = -m0;
;         const f32x16 cinit = {c, c, c, c, c, c, c, c, c, c, c, c, c, c, c, c};
;         const bf16x8 kf = lds_frag(buf + r * TROW + h * 16); sa = MFMA32(kf, a.qf[0], cinit); sb = MFMA32(kf, b.qf[0], cinit);
;     }
; #pragma unroll
;     for (int ks = 1; ks < 4; ++ks) { const bf16x8 kf = lds_frag(buf + r * TROW + (2 * ks + h) * 16); sa = MFMA32(kf, a.qf[ks], sa); sb = MFMA32(kf, b.qf[ks], sb); }
; DI void attn_b_item(unsigned char* ws, LAS unsigned char* buf, LAS unsigned char* qbuf, LAS unsigned* tbl, LAS float* km  , int bh, int qblk, int w4, int lane) {
;     ...
;             tile_lds_write(buf, tr, lane);
;             int nl = nc, Tl = Tc; bool okl = true; B_ADV(nl, Tl, okl);
;             if (okl) tile_gload(tr, K, V, nl * 256 + 32 * Tl, 1, lane);
;             {
;                 const int kb = nc * 256 + 32 * Tc;
;                 const bool own = (nc == qblk);
;                 const bool oka = own ? (Tc <= 2 * w4) : (((sela >> nc) & 1u) != 0u), okb = own ? true : (((selb >> nc) & 1u) != 0u);
;                 core2(a, b, buf, qpa - kb - 4 * h, qpb - kb - 4 * h, 1, 0x7fffffff, own && (Tc >= 2 * w4), oka, okb, m0, lane);
.LBB0_563:
	s_cmp_eq_u32 s20, s57
	s_cselect_b64 s[16:17], -1, 0
	s_and_b64 s[18:19], s[16:17], exec
	s_cselect_b32 s88, s87, 8
	s_lshl_b32 s18, -2, s20
	s_add_i32 s90, s21, 1
	s_and_b32 s82, s18, s85
	s_cmp_lg_u32 s82, 0
	s_cselect_b64 s[18:19], -1, 0
	s_ff1_i32_b32 s89, s82
	s_and_b64 s[82:83], s[18:19], exec
	s_cselect_b32 s91, s89, s20
	s_cselect_b32 vcc_lo, 0, s90
	s_cmp_lt_i32 s90, s88
	s_cselect_b64 s[82:83], -1, 0
	s_and_b64 s[88:89], s[82:83], exec
	s_cselect_b32 s88, s90, vcc_lo
	s_cselect_b32 s89, s20, s91
	s_nor_b64 s[82:83], s[82:83], s[18:19]
	v_add_u32_e32 v223, s71, v225
	s_and_b64 vcc, exec, s[82:83]
	s_waitcnt vmcnt(7)
	ds_write_b128 v223, v[152:155] offset:4608
	s_waitcnt vmcnt(6)
	ds_write_b128 v223, v[160:163] offset:5760
	s_waitcnt vmcnt(5)
	ds_write_b128 v223, v[168:171] offset:6912
	s_waitcnt vmcnt(4)
	ds_write_b128 v223, v[176:179] offset:8064
	s_lshl_b32 s18, s89, 8
	s_lshl_b32 s19, s88, 5
	s_add_i32 s18, s18, s19
	s_lshl_b32 s18, s18, 7
	v_add_u32_e32 v207, s18, v206
	global_load_dwordx4 v[152:155], v207, s[80:81]
	global_load_dwordx4 v[160:163], v207, s[80:81] offset:1024
	global_load_dwordx4 v[168:171], v207, s[80:81] offset:2048
	global_load_dwordx4 v[176:179], v207, s[80:81] offset:3072
.LBB0_565:
	s_lshl_b32 s18, s20, 8
	s_lshl_b32 s19, s21, 5
	s_add_i32 s18, s18, s19
	s_cmp_ge_i32 s21, s86
	v_or_b32_e32 v112, s18, v186
	s_cselect_b64 s[18:19], -1, 0
	s_and_b64 s[90:91], s[16:17], s[18:19]
	v_cndmask_b32_e64 v113, 0, 1, s[90:91]
	s_waitcnt vmcnt(7)
	v_mfma_f32_32x32x16_bf16 v[96:111], v[148:151], v[116:119], v[64:79]
	v_cmp_ne_u32_e64 s[18:19], 1, v113
	s_andn2_b64 vcc, exec, s[90:91]
	v_mfma_f32_32x32x16_bf16 v[80:95], v[148:151], v[132:135], v[64:79]
	s_waitcnt vmcnt(6)
	v_mfma_f32_32x32x16_bf16 v[96:111], v[156:159], v[120:123], v[96:111]
	v_mfma_f32_32x32x16_bf16 v[80:95], v[156:159], v[136:139], v[80:95]
	s_waitcnt vmcnt(5)
	v_mfma_f32_32x32x16_bf16 v[96:111], v[164:167], v[124:127], v[96:111]
	v_mfma_f32_32x32x16_bf16 v[80:95], v[164:167], v[140:143], v[80:95]
	s_waitcnt vmcnt(4)
	v_mfma_f32_32x32x16_bf16 v[96:111], v[172:175], v[128:131], v[96:111]
	v_mfma_f32_32x32x16_bf16 v[80:95], v[172:175], v[144:147], v[80:95]
	global_load_dwordx4 v[148:151], v207, s[78:79]
	global_load_dwordx4 v[156:159], v207, s[78:79] offset:1024
	global_load_dwordx4 v[164:167], v207, s[78:79] offset:2048
	global_load_dwordx4 v[172:175], v207, s[78:79] offset:3072
	s_cbranch_vccnz .LBB0_567
	v_sub_u32_e32 v113, v246, v112
	s_nop 0
	v_cmp_lt_i32_e32 vcc, -1, v113
	v_add_u32_e32 v114, -3, v113
	s_nop 5
	v_cndmask_b32_e32 v96, v245, v96, vcc
	v_cmp_lt_i32_e32 vcc, 0, v113
	s_nop 1
	v_cndmask_b32_e32 v97, v245, v97, vcc
	v_cmp_lt_i32_e32 vcc, 1, v113
	s_nop 1
	v_cndmask_b32_e32 v98, v245, v98, vcc
	v_cmp_lt_i32_e32 vcc, -1, v114
	v_add_u32_e32 v114, -9, v113
	s_nop 0
	v_cndmask_b32_e32 v99, v245, v99, vcc
	v_cmp_lt_i32_e32 vcc, 7, v113
	s_nop 1
	v_cndmask_b32_e32 v100, v245, v100, vcc
	v_cmp_lt_i32_e32 vcc, -1, v114
	v_add_u32_e32 v114, -10, v113
	s_nop 0
	v_cndmask_b32_e32 v101, v245, v101, vcc
	v_cmp_lt_i32_e32 vcc, -1, v114
	v_add_u32_e32 v114, -11, v113
	s_nop 0
	v_cndmask_b32_e32 v102, v245, v102, vcc
	v_cmp_lt_i32_e32 vcc, -1, v114
	v_subrev_u32_e32 v114, 17, v113
	s_nop 0
	v_cndmask_b32_e32 v103, v245, v103, vcc
	v_cmp_lt_i32_e32 vcc, 15, v113
	s_nop 1
	v_cndmask_b32_e32 v104, v245, v104, vcc
	v_cmp_lt_i32_e32 vcc, -1, v114
	v_subrev_u32_e32 v114, 18, v113
	s_nop 0
	v_cndmask_b32_e32 v105, v245, v105, vcc
	v_cmp_lt_i32_e32 vcc, -1, v114
	v_subrev_u32_e32 v114, 19, v113
	s_nop 0
	v_cndmask_b32_e32 v106, v245, v106, vcc
	v_cmp_lt_i32_e32 vcc, -1, v114
	v_subrev_u32_e32 v114, 24, v113
	s_nop 0
	v_cndmask_b32_e32 v107, v245, v107, vcc
	v_cmp_lt_i32_e32 vcc, -1, v114
	v_subrev_u32_e32 v114, 25, v113
	s_nop 0
	v_cndmask_b32_e32 v108, v245, v108, vcc
	v_cmp_lt_i32_e32 vcc, -1, v114
	v_subrev_u32_e32 v114, 26, v113
	v_subrev_u32_e32 v113, 27, v113
	v_cndmask_b32_e32 v109, v245, v109, vcc
	v_cmp_lt_i32_e32 vcc, -1, v114
	s_nop 1
	v_cndmask_b32_e32 v110, v245, v110, vcc
	v_cmp_lt_i32_e32 vcc, -1, v113
	s_nop 1
	v_cndmask_b32_e32 v111, v245, v111, vcc

; DI void attn_b_item(unsigned char* ws, LAS unsigned char* buf, LAS unsigned char* qbuf, LAS unsigned* tbl, LAS float* km  , int bh, int qblk, int w4, int lane) {
;     ...
;     if (cmask) {
;         int n = __builtin_ctz(cmask);
;         tile_gload(tr, K, V, n * 256, 1, lane);
.LBB0_571:
	s_waitcnt vmcnt(0)
	s_cmp_eq_u32 s56, 0
	s_cbranch_scc1 .LBB0_519
	s_ff1_i32_b32 s88, s56
	v_mbcnt_hi_u32_b32 v193, -1, v224
	v_lshlrev_b32_e32 v191, 4, v193
	v_and_b32_e32 v190, 31, v193
	v_lshrrev_b32_e32 v192, 5, v193
	v_lshlrev_b32_e32 v190, 7, v190
	v_lshl_or_b32 v190, v192, 4, v190
	s_lshl_b32 s16, s88, 15
	v_add_u32_e32 v193, s16, v191
	v_add_u32_e32 v192, s16, v190
	global_load_dwordx4 v[132:135], v193, s[80:81]
	global_load_dwordx4 v[136:139], v193, s[80:81] offset:1024
	global_load_dwordx4 v[140:143], v193, s[80:81] offset:2048
	global_load_dwordx4 v[144:147], v193, s[80:81] offset:3072
	global_load_dwordx4 v[116:119], v193, s[78:79]
	global_load_dwordx4 v[120:123], v193, s[78:79] offset:1024
	global_load_dwordx4 v[124:127], v193, s[78:79] offset:2048
	global_load_dwordx4 v[128:131], v193, s[78:79] offset:3072
	s_lshl_b32 s16, s44, 19
	s_lshl_b32 s17, s84, 22
	s_or_b32 s16, s17, s16
	s_add_u32 s82, s50, s16
	s_addc_u32 s83, s51, 0

; #define LAS __attribute__((address_space(3)))
; #define MFMA32(a, b, c) __builtin_amdgcn_mfma_f32_32x32x16_bf16((a), (b), (c), 0, 0, 0)
; DI void core1g(ASt& st, const bf16x8 (&qf)[4], LAS unsigned char* buf, bool ok, float m0, int lane) {
;     const int r = lane & 31, h = lane >> 5;
;     f32x16 s;
;     {
;         const f32x16 zero = {0.f, 0.f, 0.f, 0.f, 0.f, 0.f, 0.f, 0.f, 0.f, 0.f, 0.f, 0.f, 0.f, 0.f, 0.f, 0.f};
;         const bf16x8 kf = lds_frag(buf + r * TROW + h * 16); s = MFMA32(kf, qf[0], zero);
;     }
; #pragma unroll
;     for (int ks = 1; ks < 4; ++ks) { const bf16x8 kf = lds_frag(buf + r * TROW + (2 * ks + h) * 16); s = MFMA32(kf, qf[ks], s); }
;     LAS unsigned char* vb = buf + 32 * TROW + (4 * h + ((lane & 15) >> 2)) * TROW + 32 * ((lane >> 4) & 1) + 8 * (lane & 3);
;     softmax_p<true>(st, s, 0, 0, 0, ok, false, m0);
;     bf16x8 p[2]; pack_p(p, s, ok);
; #pragma unroll
;     for (int s2 = 0; s2 < 2; ++s2) {
;         const bf16x8 v0 = load_vfrag1(vb, 0, s2), v1 = load_vfrag1(vb, 1, s2);
;         st.o0 = MFMA32(v0, p[s2], st.o0); st.o1 = MFMA32(v1, p[s2], st.o1);
;     }
; DI void attn_b_item(unsigned char* ws, LAS unsigned char* buf, LAS unsigned char* qbuf, LAS unsigned* tbl, LAS float* km  , int bh, int qblk, int w4, int lane) {
;     ...
; #pragma unroll 1
;             for (int T = 0; T < 8; ++T) {
;                 tile_lds_write(buf, tr, lane);
;                 if (T < 7) tile_gload(tr, K, V, n * 256 + 32 * (T + 1), 1, lane);
;                 else if (nn >= 0) tile_gload(tr, K, V, nn * 256, 1, lane);
;                 core1g(g, gq, buf, okg, m0, lane);
;             }
.LBB0_580:
	s_or_b64 exec, exec, s[84:85]
	s_lshl_b32 s57, -2, s88
	s_and_b32 s57, s57, s56
	s_cmp_eq_u32 s57, 0
	s_cselect_b64 s[84:85], -1, 0
	s_cmp_lg_u32 s57, 0
	s_ff1_i32_b32 s57, s57
	s_cselect_b64 s[86:87], -1, 0
	v_add_u32_e32 v64, v228, v64
	s_waitcnt vmcnt(15)
	ds_read_b128 v[148:151], v64
	s_waitcnt vmcnt(14)
	ds_read_b128 v[152:155], v64 offset:32
	s_waitcnt vmcnt(13)
	ds_read_b128 v[156:159], v64 offset:64
	s_waitcnt vmcnt(12)
	ds_read_b128 v[160:163], v64 offset:96
	s_lshl_b32 s89, s88, 15
	s_mov_b32 s88, 0
	v_mov_b32_e32 v64, 0
	v_mov_b32_e32 v65, v112
	v_mov_b32_e32 v66, v112
	v_mov_b32_e32 v67, v112
	v_mov_b32_e32 v68, v112
	v_mov_b32_e32 v69, v112
	v_mov_b32_e32 v70, v112
	v_mov_b32_e32 v71, v112
	v_mov_b32_e32 v72, v112
	v_mov_b32_e32 v73, v112
	v_mov_b32_e32 v74, v112
	v_mov_b32_e32 v75, v112
	v_mov_b32_e32 v76, v112
	v_mov_b32_e32 v77, v112
	v_mov_b32_e32 v78, v112
	v_mov_b32_e32 v79, v112
	v_mov_b32_e32 v80, 0
	v_mov_b32_e32 v81, v112
	v_mov_b32_e32 v82, v112
	v_mov_b32_e32 v83, v112
	v_mov_b32_e32 v84, v112
	v_mov_b32_e32 v85, v112
	v_mov_b32_e32 v86, v112
	v_mov_b32_e32 v87, v112
	v_mov_b32_e32 v88, v112
	v_mov_b32_e32 v89, v112
	v_mov_b32_e32 v90, v112
	v_mov_b32_e32 v91, v112
	v_mov_b32_e32 v92, v112
	v_mov_b32_e32 v93, v112
	v_mov_b32_e32 v94, v112
	v_mov_b32_e32 v95, v112
.LBB0_581:
	s_add_i32 s90, s88, 0x1000
	s_add_i32 s90, s90, s89
	s_cmpk_eq_i32 s88, 0x7000
	s_cbranch_scc0 .Lg_off_done
	s_lshl_b32 s91, s57, 15
	s_add_i32 s90, s89, s88
	s_cmp_lg_u64 s[86:87], 0
	s_cselect_b32 s90, s91, s90
.Lg_off_done:
	s_waitcnt vmcnt(7)
	ds_write_b128 v223, v[132:135] offset:4608
	s_waitcnt vmcnt(6)
	ds_write_b128 v223, v[136:139] offset:5760
	s_waitcnt vmcnt(5)
	ds_write_b128 v223, v[140:143] offset:6912
	s_waitcnt vmcnt(4)
	ds_write_b128 v223, v[144:147] offset:8064
	v_add_u32_e32 v193, s90, v191
	v_add_u32_e32 v192, s90, v190
	global_load_dwordx4 v[132:135], v193, s[80:81]
	global_load_dwordx4 v[136:139], v193, s[80:81] offset:1024
	global_load_dwordx4 v[140:143], v193, s[80:81] offset:2048
	global_load_dwordx4 v[144:147], v193, s[80:81] offset:3072
	s_add_i32 s88, s88, 0x1000
	s_cmpk_eq_u32 s88, 0x8000
	s_waitcnt vmcnt(7)
	v_mfma_f32_32x32x16_bf16 v[96:111], v[116:119], v[148:151], 0
	s_waitcnt vmcnt(6)
	v_mfma_f32_32x32x16_bf16 v[96:111], v[120:123], v[152:155], v[96:111]
	s_waitcnt vmcnt(5)
	v_mfma_f32_32x32x16_bf16 v[96:111], v[124:127], v[156:159], v[96:111]
	ds_read_b64_tr_b16 v[164:165], v222 offset:4608
	ds_read_b64_tr_b16 v[166:167], v222 offset:5760
	s_waitcnt vmcnt(4)
	v_mfma_f32_32x32x16_bf16 v[96:111], v[128:131], v[160:163], v[96:111]
	global_load_dwordx4 v[116:119], v193, s[78:79]
	global_load_dwordx4 v[120:123], v193, s[78:79] offset:1024
	global_load_dwordx4 v[124:127], v193, s[78:79] offset:2048
	global_load_dwordx4 v[128:131], v193, s[78:79] offset:3072
	s_nop 7
	v_sub_f32_e32 v96, v96, v247
	v_sub_f32_e32 v97, v97, v247
	v_sub_f32_e32 v98, v98, v247
	v_sub_f32_e32 v99, v99, v247
	v_exp_f32_e32 v96, v96
	v_exp_f32_e32 v97, v97
	v_sub_f32_e32 v100, v100, v247
	v_sub_f32_e32 v101, v101, v247
	v_exp_f32_e32 v98, v98
	v_exp_f32_e32 v99, v99
	v_sub_f32_e32 v102, v102, v247
	v_sub_f32_e32 v103, v103, v247
	v_exp_f32_e32 v100, v100
	v_exp_f32_e32 v101, v101
	v_sub_f32_e32 v104, v104, v247
	v_sub_f32_e32 v105, v105, v247
	v_sub_f32_e32 v108, v108, v247
	v_sub_f32_e32 v109, v109, v247
	v_exp_f32_e32 v102, v102
	v_exp_f32_e32 v103, v103
	v_exp_f32_e32 v104, v104
	v_exp_f32_e32 v105, v105
	v_exp_f32_e32 v168, v108
	v_exp_f32_e32 v169, v109
	v_pk_add_f32 v[108:109], v[96:97], 0 op_sel_hi:[1,0]
	v_cvt_pk_bf16_f32 v96, v96, v97
	v_cvt_pk_bf16_f32 v97, v98, v99
	v_pk_add_f32 v[98:99], v[98:99], v[108:109]
	v_sub_f32_e32 v106, v106, v247
	v_pk_add_f32 v[98:99], v[100:101], v[98:99]
	v_sub_f32_e32 v107, v107, v247
	v_pk_add_f32 v[98:99], v[102:103], v[98:99]
	v_sub_f32_e32 v110, v110, v247
	v_pk_add_f32 v[108:109], v[104:105], v[98:99]
	v_cvt_pk_bf16_f32 v98, v100, v101
	v_cvt_pk_bf16_f32 v99, v102, v103
	ds_read_b64_tr_b16 v[102:103], v222 offset:5824
	ds_read_b64_tr_b16 v[100:101], v222 offset:4672
	v_sub_f32_e32 v111, v111, v247
	v_exp_f32_e32 v106, v106
	v_exp_f32_e32 v107, v107
	v_exp_f32_e32 v170, v110
	v_exp_f32_e32 v171, v111
	v_cndmask_b32_e64 v96, 0, v96, s[20:21]
	v_cndmask_b32_e64 v97, 0, v97, s[20:21]
	v_cndmask_b32_e64 v98, 0, v98, s[20:21]
	v_cndmask_b32_e64 v99, 0, v99, s[20:21]
	v_pk_add_f32 v[108:109], v[106:107], v[108:109]
	v_cvt_pk_bf16_f32 v104, v104, v105
	s_waitcnt lgkmcnt(2)
	v_mfma_f32_32x32x16_bf16 v[64:79], v[164:167], v[96:99], v[64:79]
	v_cvt_pk_bf16_f32 v105, v106, v107
	v_add_f32_e64 v164, v168, v108
	v_add_f32_e64 v165, v169, v109
	ds_read_b64_tr_b16 v[108:109], v222 offset:6912
	ds_read_b64_tr_b16 v[110:111], v222 offset:8064
	v_cndmask_b32_e64 v104, 0, v104, s[20:21]
	v_cndmask_b32_e64 v105, 0, v105, s[20:21]
	s_waitcnt lgkmcnt(2)
	v_mfma_f32_32x32x16_bf16 v[80:95], v[100:103], v[96:99], v[80:95]
	v_cvt_pk_bf16_f32 v96, v168, v169
	v_cndmask_b32_e64 v106, 0, v96, s[20:21]
	v_cvt_pk_bf16_f32 v96, v170, v171
	v_cndmask_b32_e64 v107, 0, v96, s[20:21]
	ds_read_b64_tr_b16 v[98:99], v222 offset:8128
	ds_read_b64_tr_b16 v[96:97], v222 offset:6976
	v_pk_add_f32 v[100:101], v[170:171], v[164:165]
	s_waitcnt lgkmcnt(2)
	v_mfma_f32_32x32x16_bf16 v[64:79], v[108:111], v[104:107], v[64:79]
	v_add_f32_e32 v100, v100, v101
	v_cndmask_b32_e64 v100, 0, v100, s[20:21]
	v_add_f32_e32 v112, v112, v100
	s_waitcnt lgkmcnt(0)
	v_mfma_f32_32x32x16_bf16 v[80:95], v[96:99], v[104:107], v[80:95]
	s_cbranch_scc1 .LBB0_589
	s_branch .LBB0_581
; #define LAS __attribute__((address_space(3)))
; DI void attn_b_item(unsigned char* ws, LAS unsigned char* buf, LAS unsigned char* qbuf, LAS unsigned* tbl, LAS float* km  , int bh, int qblk, int w4, int lane) {
;     ...
;             {
; #pragma unroll
;                 for (int g4 = 0; g4 < 4; ++g4) {
;                     *(LAS u32x4*)(buf + lane * TROW + 16 * g4) = __builtin_bit_cast(u32x4, (f32x4){g.o0[4 * g4], g.o0[4 * g4 + 1], g.o0[4 * g4 + 2], g.o0[4 * g4 + 3]});
;                     *(LAS u32x4*)(buf + lane * TROW + 64 + 16 * g4) = __builtin_bit_cast(u32x4, (f32x4){g.o1[4 * g4], g.o1[4 * g4 + 1], g.o1[4 * g4 + 2], g.o1[4 * g4 + 3]});
;                 }
;                 *(LAS u32x4*)(buf + lane * TROW + 128) = __builtin_bit_cast(u32x4, (f32x4){g.l, 0.f, 0.f, 0.f});
;                 const LAS unsigned char* ra_ = buf + ((selA ? posA : 0) + 32 * h) * TROW;
;                 const LAS unsigned char* rb_ = buf + ((selB ? posB : 0) + 32 * h) * TROW;
;                 const float fa = selA ? 1.0f : 0.f, fb = selB ? 1.0f : 0.f;
; #pragma unroll
;                 for (int g4 = 0; g4 < 4; ++g4) {
;                     const f32x4 x0 = __builtin_bit_cast(f32x4, *(const LAS u32x4*)(ra_ + 16 * g4)), x1 = __builtin_bit_cast(f32x4, *(const LAS u32x4*)(ra_ + 64 + 16 * g4));
;                     const f32x4 y0 = __builtin_bit_cast(f32x4, *(const LAS u32x4*)(rb_ + 16 * g4)), y1 = __builtin_bit_cast(f32x4, *(const LAS u32x4*)(rb_ + 64 + 16 * g4));
; #pragma unroll
;                     for (int j = 0; j < 4; ++j) {
;                         a.st.o0[4 * g4 + j] += fa * x0[j]; a.st.o1[4 * g4 + j] += fa * x1[j];
;                         b.st.o0[4 * g4 + j] += fb * y0[j]; b.st.o1[4 * g4 + j] += fb * y1[j];
;                     }
;                 }
;                 const f32x4 xl = __builtin_bit_cast(f32x4, *(const LAS u32x4*)(ra_ + 128)), yl = __builtin_bit_cast(f32x4, *(const LAS u32x4*)(rb_ + 128));
;                 a.st.l += fa * xl[0]; b.st.l += fb * yl[0];
;             }
;             if (nn < 0) break;
;             n = nn;
.LBB0_589:
	s_nop 5
	ds_write_b128 v243, v[64:67]
	s_nop 3
	ds_write_b128 v243, v[80:83] offset:64
	ds_write_b128 v243, v[68:71] offset:16
	ds_write_b128 v243, v[84:87] offset:80
	ds_write_b128 v243, v[72:75] offset:32
	ds_write_b128 v243, v[88:91] offset:96
	ds_write_b128 v243, v[76:79] offset:48
	ds_write_b128 v243, v[92:95] offset:112
	v_cndmask_b32_e64 v64, 0, v251, s[16:17]
	v_mov_b32_e32 v113, v115
	v_mov_b32_e32 v114, v115
	v_or_b32_e32 v64, v64, v226
	v_mov_b32_e32 v65, s71
	ds_write_b128 v243, v[112:115] offset:128
	v_mad_u32_u24 v113, v64, s31, v65
	v_cndmask_b32_e64 v64, 0, v250, s[18:19]
	v_add_u32_e32 v64, v64, v226
	v_mad_u32_u24 v164, v64, s31, v65
	v_cndmask_b32_e64 v112, 0, 1.0, s[16:17]
	ds_read_b128 v[64:67], v113 offset:64
	ds_read_b128 v[68:71], v113 offset:80
	ds_read_b128 v[72:75], v164 offset:80
	ds_read_b128 v[76:79], v164 offset:96
	ds_read_b128 v[80:83], v113
	ds_read_b128 v[84:87], v113 offset:16
	ds_read_b128 v[88:91], v113 offset:32
	ds_read_b128 v[92:95], v113 offset:48
	ds_read_b128 v[96:99], v113 offset:96
	ds_read_b128 v[100:103], v113 offset:112
	ds_read_b128 v[104:107], v164
	ds_read_b128 v[108:111], v164 offset:16
	ds_read_b128 v[148:151], v164 offset:32
	ds_read_b128 v[152:155], v164 offset:64
	ds_read_b128 v[156:159], v164 offset:48
	ds_read_b128 v[160:163], v164 offset:112
	s_waitcnt lgkmcnt(14)
	v_pk_fma_f32 v[32:33], v[112:113], v[64:65], v[32:33] op_sel_hi:[0,1,1]
	v_pk_fma_f32 v[34:35], v[112:113], v[66:67], v[34:35] op_sel_hi:[0,1,1]
	ds_read_b128 v[64:67], v113 offset:128
	v_pk_fma_f32 v[36:37], v[112:113], v[68:69], v[36:37] op_sel_hi:[0,1,1]
	s_waitcnt lgkmcnt(0)
	ds_read_b128 v[66:69], v164 offset:128
	v_cndmask_b32_e64 v114, 0, 1.0, s[18:19]
	v_pk_fma_f32 v[60:61], v[112:113], v[92:93], v[60:61] op_sel_hi:[0,1,1]
	v_pk_fma_f32 v[56:57], v[112:113], v[88:89], v[56:57] op_sel_hi:[0,1,1]
	v_pk_fma_f32 v[52:53], v[112:113], v[84:85], v[52:53] op_sel_hi:[0,1,1]
	v_pk_fma_f32 v[48:49], v[112:113], v[80:81], v[48:49] op_sel_hi:[0,1,1]
	v_pk_fma_f32 v[62:63], v[112:113], v[94:95], v[62:63] op_sel_hi:[0,1,1]
	v_pk_fma_f32 v[58:59], v[112:113], v[90:91], v[58:59] op_sel_hi:[0,1,1]
	v_pk_fma_f32 v[54:55], v[112:113], v[86:87], v[54:55] op_sel_hi:[0,1,1]
	v_pk_fma_f32 v[50:51], v[112:113], v[82:83], v[50:51] op_sel_hi:[0,1,1]
	v_pk_fma_f32 v[44:45], v[112:113], v[100:101], v[44:45] op_sel_hi:[0,1,1]
	v_pk_fma_f32 v[40:41], v[112:113], v[96:97], v[40:41] op_sel_hi:[0,1,1]
	v_pk_fma_f32 v[46:47], v[112:113], v[102:103], v[46:47] op_sel_hi:[0,1,1]
	v_pk_fma_f32 v[42:43], v[112:113], v[98:99], v[42:43] op_sel_hi:[0,1,1]
	v_pk_fma_f32 v[38:39], v[112:113], v[70:71], v[38:39] op_sel_hi:[0,1,1]
	v_pk_fma_f32 v[28:29], v[114:115], v[156:157], v[28:29] op_sel_hi:[0,1,1]
	v_pk_fma_f32 v[24:25], v[114:115], v[148:149], v[24:25] op_sel_hi:[0,1,1]
	v_pk_fma_f32 v[20:21], v[114:115], v[108:109], v[20:21] op_sel_hi:[0,1,1]
	v_pk_fma_f32 v[16:17], v[114:115], v[104:105], v[16:17] op_sel_hi:[0,1,1]
	v_pk_fma_f32 v[30:31], v[114:115], v[158:159], v[30:31] op_sel_hi:[0,1,1]
	v_pk_fma_f32 v[26:27], v[114:115], v[150:151], v[26:27] op_sel_hi:[0,1,1]
	v_pk_fma_f32 v[22:23], v[114:115], v[110:111], v[22:23] op_sel_hi:[0,1,1]
	v_pk_fma_f32 v[18:19], v[114:115], v[106:107], v[18:19] op_sel_hi:[0,1,1]
	v_pk_fma_f32 v[12:13], v[114:115], v[160:161], v[12:13] op_sel_hi:[0,1,1]
	v_pk_fma_f32 v[8:9], v[114:115], v[76:77], v[8:9] op_sel_hi:[0,1,1]
	v_pk_fma_f32 v[4:5], v[114:115], v[72:73], v[4:5] op_sel_hi:[0,1,1]
	v_pk_fma_f32 v[0:1], v[114:115], v[152:153], v[0:1] op_sel_hi:[0,1,1]
	v_pk_fma_f32 v[14:15], v[114:115], v[162:163], v[14:15] op_sel_hi:[0,1,1]
	v_pk_fma_f32 v[10:11], v[114:115], v[78:79], v[10:11] op_sel_hi:[0,1,1]
	v_pk_fma_f32 v[6:7], v[114:115], v[74:75], v[6:7] op_sel_hi:[0,1,1]
	v_pk_fma_f32 v[2:3], v[114:115], v[154:155], v[2:3] op_sel_hi:[0,1,1]
	v_fmac_f32_e32 v189, v112, v64
	s_waitcnt lgkmcnt(0)
	v_fmac_f32_e32 v183, v114, v66
	s_and_b64 vcc, exec, s[84:85]
	s_cbranch_vccnz .Lg_exit
	s_mov_b32 s88, s57
	s_branch .LBB0_573
.Lg_exit:
	s_waitcnt vmcnt(0)
	s_branch .LBB0_519

;     __device__ __forceinline__ void operator()(const f32x4 (&acc)[2][2][4][2], const Unit& u, int wr, int wc, int fr, int fq) const {
;         const int col0 = u.pn * 256 + wc * 32 + 8 * fq, rowbase = u.pm * 256 + wr * 64 + fr;
; #pragma unroll
;         for (int ai = 0; ai < 2; ++ai)
; #pragma unroll
;             for (int m = 0; m < 4; ++m) {
;                 const int row = rowbase + ai * 128 + m * 16; const size_t off = (size_t)row * DM + col0;
;                 float q = 0.f;
; #pragma unroll
;                 for (int bj = 0; bj < 2; ++bj) {
;                     const f32x4 r0 = *(const f32x4*)(resid + off + bj * 128), r1 = *(const f32x4*)(resid + off + bj * 128 + 4);
;                     const f32x4 o0 = r0 + acc[ai][bj][m][0], o1 = r1 + acc[ai][bj][m][1];
;                     *(f32x4*)(out + off + bj * 128) = o0; *(f32x4*)(out + off + bj * 128 + 4) = o1;
.LBB0_996:
	v_lshl_add_u32 v162, s34, 8, v146
	v_lshl_or_b32 v160, s50, 8, v148
	v_lshl_add_u32 v144, v162, 10, v160
	v_lshlrev_b32_e32 v144, 2, v144
	s_andn2_b64 vcc, exec, s[0:1]
	s_mov_b64 s[0:1], -1
	v_add_u32_e32 v248, 0x10000, v144
	v_add_u32_e32 v249, 0x20000, v144
	v_add_u32_e32 v250, 0x30000, v144
	v_add_u32_e32 v251, 0x80000, v144
	v_add_u32_e32 v252, 0x90000, v144
	v_add_u32_e32 v253, 0xa0000, v144
	v_add_u32_e32 v254, 0xb0000, v144
	global_load_dwordx4 v[152:155], v144, s[54:55]
	global_load_dwordx4 v[156:159], v144, s[54:55] offset:16
	global_load_dwordx4 v[160:163], v144, s[54:55] offset:512
	global_load_dwordx4 v[164:167], v144, s[54:55] offset:528
	global_load_dwordx4 v[168:171], v248, s[54:55]
	global_load_dwordx4 v[172:175], v248, s[54:55] offset:16
	global_load_dwordx4 v[176:179], v248, s[54:55] offset:512
	global_load_dwordx4 v[180:183], v248, s[54:55] offset:528
	global_load_dwordx4 v[184:187], v249, s[54:55]
	global_load_dwordx4 v[188:191], v249, s[54:55] offset:16
	global_load_dwordx4 v[192:195], v249, s[54:55] offset:512
	global_load_dwordx4 v[196:199], v249, s[54:55] offset:528
	global_load_dwordx4 v[200:203], v250, s[54:55]
	global_load_dwordx4 v[204:207], v250, s[54:55] offset:16
	global_load_dwordx4 v[208:211], v250, s[54:55] offset:512
	global_load_dwordx4 v[212:215], v250, s[54:55] offset:528
	global_load_dwordx4 v[216:219], v251, s[54:55]
	global_load_dwordx4 v[220:223], v251, s[54:55] offset:16
	global_load_dwordx4 v[224:227], v251, s[54:55] offset:512
	global_load_dwordx4 v[228:231], v251, s[54:55] offset:528
	global_load_dwordx4 v[232:235], v252, s[54:55]
	global_load_dwordx4 v[236:239], v252, s[54:55] offset:16
	global_load_dwordx4 v[240:243], v252, s[54:55] offset:512
	global_load_dwordx4 v[244:247], v252, s[54:55] offset:528
	s_waitcnt vmcnt(23)
	v_pk_add_f32 v[124:125], v[124:125], v[152:153]
	v_pk_add_f32 v[126:127], v[126:127], v[154:155]
	global_store_dwordx4 v144, v[124:127], s[48:49]
	s_waitcnt vmcnt(23)
	v_pk_add_f32 v[120:121], v[120:121], v[156:157]
	v_pk_add_f32 v[122:123], v[122:123], v[158:159]
	global_store_dwordx4 v144, v[120:123], s[48:49] offset:16
	s_waitcnt vmcnt(23)
	v_pk_add_f32 v[112:113], v[112:113], v[160:161]
	v_pk_add_f32 v[114:115], v[114:115], v[162:163]
	global_store_dwordx4 v144, v[112:115], s[48:49] offset:512
	s_waitcnt vmcnt(23)
	v_pk_add_f32 v[104:105], v[104:105], v[164:165]
	v_pk_add_f32 v[106:107], v[106:107], v[166:167]
	global_store_dwordx4 v144, v[104:107], s[48:49] offset:528
	s_waitcnt vmcnt(23)
	v_pk_add_f32 v[116:117], v[116:117], v[168:169]
	v_pk_add_f32 v[118:119], v[118:119], v[170:171]
	global_store_dwordx4 v248, v[116:119], s[48:49]
	s_waitcnt vmcnt(23)
	v_pk_add_f32 v[108:109], v[108:109], v[172:173]
	v_pk_add_f32 v[110:111], v[110:111], v[174:175]
	global_store_dwordx4 v248, v[108:111], s[48:49] offset:16
	s_waitcnt vmcnt(23)
	v_pk_add_f32 v[96:97], v[96:97], v[176:177]
	v_pk_add_f32 v[98:99], v[98:99], v[178:179]
	global_store_dwordx4 v248, v[96:99], s[48:49] offset:512
	s_waitcnt vmcnt(23)
	v_pk_add_f32 v[88:89], v[88:89], v[180:181]
	v_pk_add_f32 v[90:91], v[90:91], v[182:183]
	global_store_dwordx4 v248, v[88:91], s[48:49] offset:528
	global_load_dwordx4 v[152:155], v253, s[54:55]
	global_load_dwordx4 v[156:159], v253, s[54:55] offset:16
	global_load_dwordx4 v[160:163], v253, s[54:55] offset:512
	global_load_dwordx4 v[164:167], v253, s[54:55] offset:528
	global_load_dwordx4 v[168:171], v254, s[54:55]
	global_load_dwordx4 v[172:175], v254, s[54:55] offset:16
	global_load_dwordx4 v[176:179], v254, s[54:55] offset:512
	global_load_dwordx4 v[180:183], v254, s[54:55] offset:528
	s_waitcnt vmcnt(31)
	v_pk_add_f32 v[100:101], v[100:101], v[184:185]
	v_pk_add_f32 v[102:103], v[102:103], v[186:187]
	global_store_dwordx4 v249, v[100:103], s[48:49]
	s_waitcnt vmcnt(31)
;     __device__ __forceinline__ void operator()(const f32x4 (&acc)[2][2][4][2], const Unit& u, int wr, int wc, int fr, int fq) const {
;         const int col0 = u.pn * 256 + wc * 32 + 8 * fq, rowbase = u.pm * 256 + wr * 64 + fr;
; #pragma unroll
;         for (int ai = 0; ai < 2; ++ai)
; #pragma unroll
;             for (int m = 0; m < 4; ++m) {
;                 const int row = rowbase + ai * 128 + m * 16; const size_t off = (size_t)row * DM + col0;
;                 float q = 0.f;
; #pragma unroll
;                 for (int bj = 0; bj < 2; ++bj) {
;                     const f32x4 r0 = *(const f32x4*)(resid + off + bj * 128), r1 = *(const f32x4*)(resid + off + bj * 128 + 4);
;                     const f32x4 o0 = r0 + acc[ai][bj][m][0], o1 = r1 + acc[ai][bj][m][1];
;                     *(f32x4*)(out + off + bj * 128) = o0; *(f32x4*)(out + off + bj * 128 + 4) = o1;
	v_pk_add_f32 v[92:93], v[92:93], v[188:189]
	v_pk_add_f32 v[94:95], v[94:95], v[190:191]
	global_store_dwordx4 v249, v[92:95], s[48:49] offset:16
	s_waitcnt vmcnt(31)
	v_pk_add_f32 v[80:81], v[80:81], v[192:193]
	v_pk_add_f32 v[82:83], v[82:83], v[194:195]
	global_store_dwordx4 v249, v[80:83], s[48:49] offset:512
	s_waitcnt vmcnt(31)
	v_pk_add_f32 v[72:73], v[72:73], v[196:197]
	v_pk_add_f32 v[74:75], v[74:75], v[198:199]
	global_store_dwordx4 v249, v[72:75], s[48:49] offset:528
	s_waitcnt vmcnt(31)
	v_pk_add_f32 v[84:85], v[84:85], v[200:201]
	v_pk_add_f32 v[86:87], v[86:87], v[202:203]
	global_store_dwordx4 v250, v[84:87], s[48:49]
	s_waitcnt vmcnt(31)
	v_pk_add_f32 v[76:77], v[76:77], v[204:205]
	v_pk_add_f32 v[78:79], v[78:79], v[206:207]
	global_store_dwordx4 v250, v[76:79], s[48:49] offset:16
	s_waitcnt vmcnt(31)
	v_pk_add_f32 v[68:69], v[68:69], v[208:209]
	v_pk_add_f32 v[70:71], v[70:71], v[210:211]
	global_store_dwordx4 v250, v[68:71], s[48:49] offset:512
	s_waitcnt vmcnt(31)
	v_pk_add_f32 v[64:65], v[64:65], v[212:213]
	v_pk_add_f32 v[66:67], v[66:67], v[214:215]
	global_store_dwordx4 v250, v[64:67], s[48:49] offset:528
	s_waitcnt vmcnt(31)
	v_pk_add_f32 v[60:61], v[60:61], v[216:217]
	v_pk_add_f32 v[62:63], v[62:63], v[218:219]
	global_store_dwordx4 v251, v[60:63], s[48:49]
	s_waitcnt vmcnt(31)
	v_pk_add_f32 v[56:57], v[56:57], v[220:221]
	v_pk_add_f32 v[58:59], v[58:59], v[222:223]
	global_store_dwordx4 v251, v[56:59], s[48:49] offset:16
	s_waitcnt vmcnt(31)
	v_pk_add_f32 v[48:49], v[48:49], v[224:225]
	v_pk_add_f32 v[50:51], v[50:51], v[226:227]
	global_store_dwordx4 v251, v[48:51], s[48:49] offset:512
	s_waitcnt vmcnt(31)
	v_pk_add_f32 v[40:41], v[40:41], v[228:229]
	v_pk_add_f32 v[42:43], v[42:43], v[230:231]
	global_store_dwordx4 v251, v[40:43], s[48:49] offset:528
	s_waitcnt vmcnt(31)
	v_pk_add_f32 v[52:53], v[52:53], v[232:233]
	v_pk_add_f32 v[54:55], v[54:55], v[234:235]
	global_store_dwordx4 v252, v[52:55], s[48:49]
	s_waitcnt vmcnt(31)
	v_pk_add_f32 v[44:45], v[44:45], v[236:237]
	v_pk_add_f32 v[46:47], v[46:47], v[238:239]
	global_store_dwordx4 v252, v[44:47], s[48:49] offset:16
	s_waitcnt vmcnt(31)
	v_pk_add_f32 v[32:33], v[32:33], v[240:241]
	v_pk_add_f32 v[34:35], v[34:35], v[242:243]
	global_store_dwordx4 v252, v[32:35], s[48:49] offset:512
	s_waitcnt vmcnt(31)
	v_pk_add_f32 v[24:25], v[24:25], v[244:245]
	v_pk_add_f32 v[26:27], v[26:27], v[246:247]
	global_store_dwordx4 v252, v[24:27], s[48:49] offset:528
	s_waitcnt vmcnt(23)
	v_pk_add_f32 v[36:37], v[36:37], v[152:153]
	v_pk_add_f32 v[38:39], v[38:39], v[154:155]
	global_store_dwordx4 v253, v[36:39], s[48:49]
	s_waitcnt vmcnt(23)
	v_pk_add_f32 v[28:29], v[28:29], v[156:157]
	v_pk_add_f32 v[30:31], v[30:31], v[158:159]
	global_store_dwordx4 v253, v[28:31], s[48:49] offset:16
	s_waitcnt vmcnt(23)
	v_pk_add_f32 v[16:17], v[16:17], v[160:161]
	v_pk_add_f32 v[18:19], v[18:19], v[162:163]
	global_store_dwordx4 v253, v[16:19], s[48:49] offset:512
	s_waitcnt vmcnt(23)
	v_pk_add_f32 v[8:9], v[8:9], v[164:165]
	v_pk_add_f32 v[10:11], v[10:11], v[166:167]
	global_store_dwordx4 v253, v[8:11], s[48:49] offset:528
	s_waitcnt vmcnt(23)
	v_pk_add_f32 v[20:21], v[20:21], v[168:169]
	v_pk_add_f32 v[22:23], v[22:23], v[170:171]
	global_store_dwordx4 v254, v[20:23], s[48:49]
	s_waitcnt vmcnt(23)
	v_pk_add_f32 v[12:13], v[12:13], v[172:173]
	v_pk_add_f32 v[14:15], v[14:15], v[174:175]
	global_store_dwordx4 v254, v[12:15], s[48:49] offset:16
	s_waitcnt vmcnt(23)
	v_pk_add_f32 v[4:5], v[4:5], v[176:177]
	v_pk_add_f32 v[6:7], v[6:7], v[178:179]
	global_store_dwordx4 v254, v[4:7], s[48:49] offset:512
	s_waitcnt vmcnt(23)
	v_pk_add_f32 v[0:1], v[0:1], v[180:181]
	v_pk_add_f32 v[2:3], v[2:3], v[182:183]
	global_store_dwordx4 v254, v[0:3], s[48:49] offset:528
	s_cbranch_vccnz .LBB0_985
	s_andn2_b64 vcc, exec, s[4:5]
	s_cbranch_vccnz .LBB0_984
	s_barrier
	s_branch .LBB0_984
